# v38 + convert_weights transpose loops software-pipelined: 16 weight loads issued back to back per iteration, LDS writes afterwards with counted waits (compiler had 16 serial load->write round trips pe
# baseline (speedup 1.0000x reference)
; __device__ __forceinline__ void transpose_item(const float* W, int K, int N, bf16_t* WT, int mode, float* scr, int item, int lane) {
;     ...
; #pragma unroll 8
;     for (int i = 0; i < 32; ++i) { const int kk = 2 * i + (lane >> 5); scr[kk * 33 + (lane & 31)] = W[(size_t)(k0 + kk) * N + n0 + (lane & 31)]; }
;     asm volatile("s_waitcnt lgkmcnt(0)" ::: "memory");
.LBB0_84:
	s_lshl_b32 s13, s9, 1
	s_lshl_b32 s12, s8, 1
	v_or_b32_e32 v128, s13, v22
	v_or_b32_e32 v34, s12, v3
	v_mov_b32_e32 v35, v129
	v_lshlrev_b64 v[36:37], 12, v[128:129]
	v_lshlrev_b64 v[34:35], 12, v[34:35]
	v_lshl_add_u64 v[36:37], v[20:21], 0, v[36:37]
	v_lshl_add_u64 v[34:35], v[20:21], 0, v[34:35]
	global_load_dword v64, v[36:37], off
	global_load_dword v65, v[34:35], off
	v_or_b32_e32 v25, s12, v1
	v_or_b32_e32 v26, s13, v0
	v_mad_u64_u32 v[66:67], s[18:19], v26, s16, v[2:3]
	v_mad_u64_u32 v[68:69], s[18:19], v25, s16, v[2:3]
	s_add_i32 s19, s13, 4
	s_add_i32 s18, s12, 4
	v_or_b32_e32 v128, s19, v22
	v_mov_b32_e32 v35, v129
	v_or_b32_e32 v25, s18, v1
	v_or_b32_e32 v26, s19, v0
	s_add_i32 s9, s9, 16
	s_add_i32 s8, s8, 16
	s_add_i32 s15, s15, -16
	v_or_b32_e32 v34, s18, v3
	v_lshlrev_b64 v[36:37], 12, v[128:129]
	v_lshlrev_b64 v[34:35], 12, v[34:35]
	v_lshl_add_u64 v[36:37], v[20:21], 0, v[36:37]
	v_lshl_add_u64 v[34:35], v[20:21], 0, v[34:35]
	global_load_dword v70, v[36:37], off
	global_load_dword v71, v[34:35], off
	v_mad_u64_u32 v[72:73], s[18:19], v26, s16, v[2:3]
	v_mad_u64_u32 v[74:75], s[18:19], v25, s16, v[2:3]
	s_add_i32 s19, s13, 8
	s_add_i32 s18, s12, 8
	v_or_b32_e32 v128, s19, v22
	v_mov_b32_e32 v35, v129
	v_or_b32_e32 v25, s18, v1
	v_or_b32_e32 v26, s19, v0
	v_or_b32_e32 v34, s18, v3
	v_lshlrev_b64 v[36:37], 12, v[128:129]
	v_lshlrev_b64 v[34:35], 12, v[34:35]
	v_lshl_add_u64 v[36:37], v[20:21], 0, v[36:37]
	v_lshl_add_u64 v[34:35], v[20:21], 0, v[34:35]
	global_load_dword v76, v[36:37], off
	global_load_dword v77, v[34:35], off
	v_mad_u64_u32 v[78:79], s[18:19], v26, s16, v[2:3]
	v_mad_u64_u32 v[80:81], s[18:19], v25, s16, v[2:3]
	s_add_i32 s19, s13, 12
	s_add_i32 s18, s12, 12
	v_or_b32_e32 v128, s19, v22
	v_mov_b32_e32 v35, v129
	v_or_b32_e32 v25, s18, v1
	v_or_b32_e32 v26, s19, v0
	v_or_b32_e32 v34, s18, v3
	v_lshlrev_b64 v[36:37], 12, v[128:129]
	v_lshlrev_b64 v[34:35], 12, v[34:35]
	v_lshl_add_u64 v[36:37], v[20:21], 0, v[36:37]
	v_lshl_add_u64 v[34:35], v[20:21], 0, v[34:35]
	global_load_dword v82, v[36:37], off
	global_load_dword v83, v[34:35], off
	v_mad_u64_u32 v[84:85], s[18:19], v26, s16, v[2:3]
	v_mad_u64_u32 v[86:87], s[18:19], v25, s16, v[2:3]
	s_add_i32 s19, s13, 16
	s_add_i32 s18, s12, 16
	v_or_b32_e32 v128, s19, v22
	v_mov_b32_e32 v35, v129
	v_or_b32_e32 v25, s18, v1
	v_or_b32_e32 v26, s19, v0
	v_or_b32_e32 v34, s18, v3
	v_lshlrev_b64 v[36:37], 12, v[128:129]
	v_lshlrev_b64 v[34:35], 12, v[34:35]
	v_lshl_add_u64 v[36:37], v[20:21], 0, v[36:37]
	v_lshl_add_u64 v[34:35], v[20:21], 0, v[34:35]
	global_load_dword v88, v[36:37], off
	global_load_dword v89, v[34:35], off
	v_mad_u64_u32 v[90:91], s[18:19], v26, s16, v[2:3]
	v_mad_u64_u32 v[92:93], s[18:19], v25, s16, v[2:3]
	s_add_i32 s19, s13, 20
	s_add_i32 s18, s12, 20
	v_or_b32_e32 v128, s19, v22
	v_mov_b32_e32 v35, v129
	v_or_b32_e32 v25, s18, v1
	v_or_b32_e32 v26, s19, v0
	v_or_b32_e32 v34, s18, v3
	v_lshlrev_b64 v[36:37], 12, v[128:129]
	v_lshlrev_b64 v[34:35], 12, v[34:35]
	v_lshl_add_u64 v[36:37], v[20:21], 0, v[36:37]
	v_lshl_add_u64 v[34:35], v[20:21], 0, v[34:35]
	global_load_dword v94, v[36:37], off
	global_load_dword v95, v[34:35], off
	v_mad_u64_u32 v[96:97], s[18:19], v26, s16, v[2:3]
	v_mad_u64_u32 v[98:99], s[18:19], v25, s16, v[2:3]
	s_add_i32 s19, s13, 24
	s_add_i32 s18, s12, 24
	v_or_b32_e32 v128, s19, v22
	v_mov_b32_e32 v35, v129
	v_or_b32_e32 v25, s18, v1
	v_or_b32_e32 v26, s19, v0
	s_add_i32 s13, s13, 28
	s_add_i32 s12, s12, 28
	s_cmp_lg_u32 s15, 0
	v_or_b32_e32 v34, s18, v3
	v_lshlrev_b64 v[36:37], 12, v[128:129]
	v_lshlrev_b64 v[34:35], 12, v[34:35]
	v_lshl_add_u64 v[36:37], v[20:21], 0, v[36:37]
	v_lshl_add_u64 v[34:35], v[20:21], 0, v[34:35]
	global_load_dword v100, v[36:37], off
	global_load_dword v101, v[34:35], off
	v_mad_u64_u32 v[102:103], s[18:19], v26, s16, v[2:3]
	v_mad_u64_u32 v[104:105], s[18:19], v25, s16, v[2:3]
	v_or_b32_e32 v128, s13, v22
	v_mov_b32_e32 v35, v129
	v_or_b32_e32 v26, s13, v0
	v_or_b32_e32 v25, s12, v1
	v_or_b32_e32 v34, s12, v3
	v_lshlrev_b64 v[36:37], 12, v[128:129]
	v_lshlrev_b64 v[34:35], 12, v[34:35]
	v_lshl_add_u64 v[36:37], v[20:21], 0, v[36:37]
	v_lshl_add_u64 v[34:35], v[20:21], 0, v[34:35]
	global_load_dword v106, v[36:37], off
	global_load_dword v107, v[34:35], off
	v_mad_u64_u32 v[108:109], s[12:13], v26, s16, v[2:3]
	v_mad_u64_u32 v[110:111], s[12:13], v25, s16, v[2:3]
	s_waitcnt vmcnt(15)
	ds_write_b32 v66, v64
	s_waitcnt vmcnt(14)
	ds_write_b32 v68, v65
	s_waitcnt vmcnt(13)
	ds_write_b32 v72, v70
	s_waitcnt vmcnt(12)
	ds_write_b32 v74, v71
	s_waitcnt vmcnt(11)
	ds_write_b32 v78, v76
	s_waitcnt vmcnt(10)
	ds_write_b32 v80, v77
	s_waitcnt vmcnt(9)
	ds_write_b32 v84, v82
	s_waitcnt vmcnt(8)
	ds_write_b32 v86, v83
	s_waitcnt vmcnt(7)
	ds_write_b32 v90, v88
	s_waitcnt vmcnt(6)
	ds_write_b32 v92, v89
	s_waitcnt vmcnt(5)
	ds_write_b32 v96, v94
	s_waitcnt vmcnt(4)
	ds_write_b32 v98, v95
	s_waitcnt vmcnt(3)
	ds_write_b32 v102, v100
	s_waitcnt vmcnt(2)
	ds_write_b32 v104, v101
	s_waitcnt vmcnt(1)
	ds_write_b32 v108, v106
	s_waitcnt vmcnt(0)
	ds_write_b32 v110, v107
	s_cbranch_scc1 .LBB0_84
; __device__ __forceinline__ unsigned pk2(float lo, float hi) { f32x2_t v = {lo, hi}; bf16x2_t b = __builtin_convertvector(v, bf16x2_t); return __builtin_bit_cast(unsigned, b); }
; __device__ __forceinline__ void transpose_item(const float* W, int K, int N, bf16_t* WT, int mode, float* scr, int item, int lane) {
;     ...
;     const int c = lane & 7;
; #pragma unroll
;     for (int j = 0; j < 4; ++j) { const int n = (lane >> 3) + 8 * j; const float* s = scr + (8 * c) * 33 + n;
;         u32x4 o; o.x = pk2(s[0 * 33], s[1 * 33]); o.y = pk2(s[2 * 33], s[3 * 33]); o.z = pk2(s[4 * 33], s[5 * 33]); o.w = pk2(s[6 * 33], s[7 * 33]);
;         *(u32x4*)(WT + (size_t)(r0 + n) * K + k0 + 8 * c) = o; }
;     asm volatile("s_waitcnt lgkmcnt(0)" ::: "memory");
	s_waitcnt lgkmcnt(0)
	v_lshlrev_b32_e32 v128, 1, v24
	ds_read2_b32 v[20:21], v29 offset0:33 offset1:41
	ds_read2_b32 v[24:25], v29 offset1:8
	ds_read2_b32 v[38:39], v29 offset0:66 offset1:74
	ds_read2_b32 v[40:41], v29 offset0:99 offset1:107
	ds_read2_b32 v[42:43], v29 offset0:132 offset1:140
	ds_read2_b32 v[44:45], v29 offset0:165 offset1:173
	ds_read2_b32 v[46:47], v29 offset0:198 offset1:206
	ds_read2_b32 v[48:49], v29 offset0:231 offset1:239
	v_or_b32_e32 v3, v23, v28
	v_mul_u32_u24_e32 v3, 0xb00, v3
	v_lshl_add_u64 v[50:51], v[4:5], 0, v[128:129]
	v_lshlrev_b32_e32 v128, 1, v3
	s_waitcnt lgkmcnt(6)
	v_cvt_pk_bf16_f32 v34, v24, v20
	s_waitcnt lgkmcnt(4)
	v_cvt_pk_bf16_f32 v35, v38, v40
	s_waitcnt lgkmcnt(2)
	v_cvt_pk_bf16_f32 v36, v42, v44
	s_waitcnt lgkmcnt(0)
	v_cvt_pk_bf16_f32 v37, v46, v48
	v_lshl_add_u64 v[52:53], v[50:51], 0, v[128:129]
	global_store_dwordx4 v[52:53], v[34:37], off
	v_or_b32_e32 v3, v23, v30
	v_mul_u32_u24_e32 v3, 0xb00, v3
	v_cvt_pk_bf16_f32 v34, v25, v21
	v_cvt_pk_bf16_f32 v35, v39, v41
	v_cvt_pk_bf16_f32 v36, v43, v45
	v_cvt_pk_bf16_f32 v37, v47, v49
	ds_read2_b32 v[24:25], v29 offset0:16 offset1:24
	ds_read2_b32 v[38:39], v29 offset0:49 offset1:57
	ds_read2_b32 v[40:41], v29 offset0:82 offset1:90
	ds_read2_b32 v[42:43], v29 offset0:115 offset1:123
	ds_read2_b32 v[44:45], v29 offset0:148 offset1:156
	ds_read2_b32 v[46:47], v29 offset0:181 offset1:189
	ds_read2_b32 v[48:49], v29 offset0:214 offset1:222
	ds_read2_b32 v[52:53], v29 offset0:247 offset1:255
	v_lshlrev_b32_e32 v128, 1, v3
	v_or_b32_e32 v3, v23, v31
	v_mul_u32_u24_e32 v3, 0xb00, v3
	v_lshl_add_u64 v[20:21], v[50:51], 0, v[128:129]
	v_lshlrev_b32_e32 v128, 1, v3
	v_or_b32_e32 v3, v23, v32
	v_mul_u32_u24_e32 v3, 0xb00, v3
	global_store_dwordx4 v[20:21], v[34:37], off
	v_lshl_add_u64 v[20:21], v[50:51], 0, v[128:129]
	v_lshlrev_b32_e32 v128, 1, v3
	s_waitcnt lgkmcnt(6)
	v_cvt_pk_bf16_f32 v34, v24, v38
	s_waitcnt lgkmcnt(4)
	v_cvt_pk_bf16_f32 v35, v40, v42
	s_waitcnt lgkmcnt(2)
	v_cvt_pk_bf16_f32 v36, v44, v46
	s_waitcnt lgkmcnt(0)
	v_cvt_pk_bf16_f32 v37, v48, v52
	global_store_dwordx4 v[20:21], v[34:37], off
	v_lshl_add_u64 v[20:21], v[50:51], 0, v[128:129]
	s_nop 0
	v_cvt_pk_bf16_f32 v34, v25, v39
	v_cvt_pk_bf16_f32 v35, v41, v43
	v_cvt_pk_bf16_f32 v36, v45, v47
	v_cvt_pk_bf16_f32 v37, v49, v53
	global_store_dwordx4 v[20:21], v[34:37], off
	s_waitcnt lgkmcnt(0)

; __device__ __forceinline__ unsigned pk2(float lo, float hi) { f32x2_t v = {lo, hi}; bf16x2_t b = __builtin_convertvector(v, bf16x2_t); return __builtin_bit_cast(unsigned, b); }
; __device__ __forceinline__ void transpose_item(const float* W, int K, int N, bf16_t* WT, int mode, float* scr, int item, int lane) {
;     ...
; #pragma unroll 8
;     for (int i = 0; i < 32; ++i) { const int kk = 2 * i + (lane >> 5); scr[kk * 33 + (lane & 31)] = W[(size_t)(k0 + kk) * N + n0 + (lane & 31)]; }
;     asm volatile("s_waitcnt lgkmcnt(0)" ::: "memory");
;     const int c = lane & 7;
; #pragma unroll
;     for (int j = 0; j < 4; ++j) { const int n = (lane >> 3) + 8 * j; const float* s = scr + (8 * c) * 33 + n;
;         u32x4 o; o.x = pk2(s[0 * 33], s[1 * 33]); o.y = pk2(s[2 * 33], s[3 * 33]); o.z = pk2(s[4 * 33], s[5 * 33]); o.w = pk2(s[6 * 33], s[7 * 33]);
;         *(u32x4*)(WT + (size_t)(r0 + n) * K + k0 + 8 * c) = o; }
;     asm volatile("s_waitcnt lgkmcnt(0)" ::: "memory");
.LBB0_92:
	s_lshl_b32 s15, s9, 1
	s_lshl_b32 s13, s8, 1
	v_or_b32_e32 v34, s15, v22
	v_or_b32_e32 v33, s13, v3
	v_mad_u64_u32 v[34:35], s[18:19], v34, s17, v[20:21]
	v_mad_u64_u32 v[36:37], s[18:19], v33, s17, v[20:21]
	global_load_dword v64, v[34:35], off
	global_load_dword v65, v[36:37], off
	v_or_b32_e32 v25, s13, v1
	v_or_b32_e32 v26, s15, v0
	v_mad_u64_u32 v[66:67], s[18:19], v26, s16, v[2:3]
	v_mad_u64_u32 v[68:69], s[18:19], v25, s16, v[2:3]
	s_add_i32 s19, s15, 4
	s_add_i32 s18, s13, 4
	v_or_b32_e32 v25, s18, v1
	v_or_b32_e32 v26, s19, v0
	s_add_i32 s9, s9, 16
	s_add_i32 s8, s8, 16
	s_add_i32 s12, s12, -16
	v_or_b32_e32 v34, s19, v22
	v_or_b32_e32 v33, s18, v3
	v_mad_u64_u32 v[34:35], s[18:19], v34, s17, v[20:21]
	v_mad_u64_u32 v[36:37], s[18:19], v33, s17, v[20:21]
	global_load_dword v70, v[34:35], off
	global_load_dword v71, v[36:37], off
	v_mad_u64_u32 v[72:73], s[18:19], v26, s16, v[2:3]
	v_mad_u64_u32 v[74:75], s[18:19], v25, s16, v[2:3]
	s_add_i32 s19, s15, 8
	s_add_i32 s18, s13, 8
	v_or_b32_e32 v25, s18, v1
	v_or_b32_e32 v26, s19, v0
	v_or_b32_e32 v34, s19, v22
	v_or_b32_e32 v33, s18, v3
	v_mad_u64_u32 v[34:35], s[18:19], v34, s17, v[20:21]
	v_mad_u64_u32 v[36:37], s[18:19], v33, s17, v[20:21]
	global_load_dword v76, v[34:35], off
	global_load_dword v77, v[36:37], off
	v_mad_u64_u32 v[78:79], s[18:19], v26, s16, v[2:3]
	v_mad_u64_u32 v[80:81], s[18:19], v25, s16, v[2:3]
	s_add_i32 s19, s15, 12
	s_add_i32 s18, s13, 12
	v_or_b32_e32 v25, s18, v1
	v_or_b32_e32 v26, s19, v0
	v_or_b32_e32 v34, s19, v22
	v_or_b32_e32 v33, s18, v3
	v_mad_u64_u32 v[34:35], s[18:19], v34, s17, v[20:21]
	v_mad_u64_u32 v[36:37], s[18:19], v33, s17, v[20:21]
	global_load_dword v82, v[34:35], off
	global_load_dword v83, v[36:37], off
	v_mad_u64_u32 v[84:85], s[18:19], v26, s16, v[2:3]
	v_mad_u64_u32 v[86:87], s[18:19], v25, s16, v[2:3]
	s_add_i32 s19, s15, 16
	s_add_i32 s18, s13, 16
	v_or_b32_e32 v25, s18, v1
	v_or_b32_e32 v26, s19, v0
	v_or_b32_e32 v34, s19, v22
	v_or_b32_e32 v33, s18, v3
	v_mad_u64_u32 v[34:35], s[18:19], v34, s17, v[20:21]
	v_mad_u64_u32 v[36:37], s[18:19], v33, s17, v[20:21]
	global_load_dword v88, v[34:35], off
	global_load_dword v89, v[36:37], off
	v_mad_u64_u32 v[90:91], s[18:19], v26, s16, v[2:3]
	v_mad_u64_u32 v[92:93], s[18:19], v25, s16, v[2:3]
	s_add_i32 s19, s15, 20
	s_add_i32 s18, s13, 20
	v_or_b32_e32 v25, s18, v1
	v_or_b32_e32 v26, s19, v0
	v_or_b32_e32 v34, s19, v22
	v_or_b32_e32 v33, s18, v3
	v_mad_u64_u32 v[34:35], s[18:19], v34, s17, v[20:21]
	v_mad_u64_u32 v[36:37], s[18:19], v33, s17, v[20:21]
	global_load_dword v94, v[34:35], off
	global_load_dword v95, v[36:37], off
	v_mad_u64_u32 v[96:97], s[18:19], v26, s16, v[2:3]
	v_mad_u64_u32 v[98:99], s[18:19], v25, s16, v[2:3]
	s_add_i32 s19, s15, 24
	s_add_i32 s18, s13, 24
	v_or_b32_e32 v25, s18, v1
	v_or_b32_e32 v26, s19, v0
	s_add_i32 s15, s15, 28
	s_add_i32 s13, s13, 28
	s_cmp_lg_u32 s12, 0
	v_or_b32_e32 v34, s19, v22
	v_or_b32_e32 v33, s18, v3
	v_mad_u64_u32 v[34:35], s[18:19], v34, s17, v[20:21]
	v_mad_u64_u32 v[36:37], s[18:19], v33, s17, v[20:21]
	global_load_dword v100, v[34:35], off
	global_load_dword v101, v[36:37], off
	v_mad_u64_u32 v[102:103], s[18:19], v26, s16, v[2:3]
	v_mad_u64_u32 v[104:105], s[18:19], v25, s16, v[2:3]
	v_or_b32_e32 v26, s15, v0
	v_or_b32_e32 v25, s13, v1
	v_or_b32_e32 v34, s15, v22
	v_or_b32_e32 v33, s13, v3
	v_mad_u64_u32 v[34:35], s[18:19], v34, s17, v[20:21]
	v_mad_u64_u32 v[36:37], s[18:19], v33, s17, v[20:21]
	global_load_dword v106, v[34:35], off
	global_load_dword v107, v[36:37], off
	v_mad_u64_u32 v[108:109], s[18:19], v26, s16, v[2:3]
	v_mad_u64_u32 v[110:111], s[18:19], v25, s16, v[2:3]
	s_waitcnt vmcnt(15)
	ds_write_b32 v66, v64
	s_waitcnt vmcnt(14)
	ds_write_b32 v68, v65
	s_waitcnt vmcnt(13)
	ds_write_b32 v72, v70
	s_waitcnt vmcnt(12)
	ds_write_b32 v74, v71
	s_waitcnt vmcnt(11)
	ds_write_b32 v78, v76
	s_waitcnt vmcnt(10)
	ds_write_b32 v80, v77
	s_waitcnt vmcnt(9)
	ds_write_b32 v84, v82
	s_waitcnt vmcnt(8)
	ds_write_b32 v86, v83
	s_waitcnt vmcnt(7)
	ds_write_b32 v90, v88
	s_waitcnt vmcnt(6)
	ds_write_b32 v92, v89
	s_waitcnt vmcnt(5)
	ds_write_b32 v96, v94
	s_waitcnt vmcnt(4)
	ds_write_b32 v98, v95
	s_waitcnt vmcnt(3)
	ds_write_b32 v102, v100
	s_waitcnt vmcnt(2)
	ds_write_b32 v104, v101
	s_waitcnt vmcnt(1)
	ds_write_b32 v108, v106
	s_waitcnt vmcnt(0)
	ds_write_b32 v110, v107
	s_cbranch_scc1 .LBB0_92
	s_waitcnt lgkmcnt(0)
	v_lshlrev_b32_e32 v128, 1, v24
	ds_read2_b32 v[20:21], v29 offset0:33 offset1:41
	ds_read2_b32 v[24:25], v29 offset1:8
	ds_read2_b32 v[38:39], v29 offset0:66 offset1:74
	ds_read2_b32 v[40:41], v29 offset0:99 offset1:107
	ds_read2_b32 v[42:43], v29 offset0:132 offset1:140
	ds_read2_b32 v[44:45], v29 offset0:165 offset1:173
	ds_read2_b32 v[46:47], v29 offset0:198 offset1:206
	ds_read2_b32 v[48:49], v29 offset0:231 offset1:239
	v_lshl_add_u64 v[50:51], v[6:7], 0, v[128:129]
	v_add_u32_e32 v128, v23, v28
	v_lshlrev_b64 v[52:53], 11, v[128:129]
	s_waitcnt lgkmcnt(6)
	v_cvt_pk_bf16_f32 v34, v24, v20
	s_waitcnt lgkmcnt(4)
	v_cvt_pk_bf16_f32 v35, v38, v40
	s_waitcnt lgkmcnt(2)
	v_cvt_pk_bf16_f32 v36, v42, v44
	s_waitcnt lgkmcnt(0)
	v_cvt_pk_bf16_f32 v37, v46, v48
	v_lshl_add_u64 v[52:53], v[50:51], 0, v[52:53]
	global_store_dwordx4 v[52:53], v[34:37], off
	v_add_u32_e32 v128, v23, v30
	s_nop 0
	v_cvt_pk_bf16_f32 v34, v25, v21
	v_cvt_pk_bf16_f32 v35, v39, v41
	v_cvt_pk_bf16_f32 v36, v43, v45
	v_cvt_pk_bf16_f32 v37, v47, v49
	ds_read2_b32 v[24:25], v29 offset0:49 offset1:57
	ds_read2_b32 v[38:39], v29 offset0:16 offset1:24
	ds_read2_b32 v[40:41], v29 offset0:82 offset1:90
	ds_read2_b32 v[42:43], v29 offset0:115 offset1:123
	ds_read2_b32 v[44:45], v29 offset0:148 offset1:156
	ds_read2_b32 v[46:47], v29 offset0:181 offset1:189
	ds_read2_b32 v[48:49], v29 offset0:214 offset1:222
	ds_read2_b32 v[52:53], v29 offset0:247 offset1:255
	v_lshlrev_b64 v[20:21], 11, v[128:129]
	v_lshl_add_u64 v[20:21], v[50:51], 0, v[20:21]
	v_add_u32_e32 v128, v23, v31
	global_store_dwordx4 v[20:21], v[34:37], off
	v_lshlrev_b64 v[20:21], 11, v[128:129]
	v_lshl_add_u64 v[20:21], v[50:51], 0, v[20:21]
	s_waitcnt lgkmcnt(6)
	v_cvt_pk_bf16_f32 v34, v38, v24
	s_waitcnt lgkmcnt(4)
	v_cvt_pk_bf16_f32 v35, v40, v42
	s_waitcnt lgkmcnt(2)
	v_cvt_pk_bf16_f32 v36, v44, v46
	s_waitcnt lgkmcnt(0)
	v_cvt_pk_bf16_f32 v37, v48, v52
	v_add_u32_e32 v128, v23, v32
	global_store_dwordx4 v[20:21], v[34:37], off
	v_lshlrev_b64 v[20:21], 11, v[128:129]
	v_lshl_add_u64 v[20:21], v[50:51], 0, v[20:21]
	v_cvt_pk_bf16_f32 v34, v39, v25
	v_cvt_pk_bf16_f32 v35, v41, v43
	v_cvt_pk_bf16_f32 v36, v45, v47
	v_cvt_pk_bf16_f32 v37, v49, v53
	global_store_dwordx4 v[20:21], v[34:37], off
	s_waitcnt lgkmcnt(0)
	s_or_b64 exec, exec, s[38:39]

; __device__ __forceinline__ void transpose_item(const float* W, int K, int N, bf16_t* WT, int mode, float* scr, int item, int lane) {
;     const int nblk = N / 32, kb = item / nblk, nb = item % nblk, k0 = 64 * kb, n0 = 32 * nb;
;     int r0 = n0;
;     if (mode == 1) { r0 = (n0 < FFH) ? (n0 / 128) * 256 + (n0 % 128) : ((n0 - FFH) / 128) * 256 + 128 + ((n0 - FFH) % 128); }
; #pragma unroll 8
;     for (int i = 0; i < 32; ++i) { const int kk = 2 * i + (lane >> 5); scr[kk * 33 + (lane & 31)] = W[(size_t)(k0 + kk) * N + n0 + (lane & 31)]; }
.LBB0_96:
	s_lshl_b32 s13, s9, 1
	s_lshl_b32 s12, s8, 1
	v_or_b32_e32 v128, s13, v22
	v_or_b32_e32 v34, s12, v3
	v_mov_b32_e32 v35, v129
	v_lshlrev_b64 v[36:37], 12, v[128:129]
	v_lshlrev_b64 v[34:35], 12, v[34:35]
	v_lshl_add_u64 v[36:37], v[20:21], 0, v[36:37]
	v_lshl_add_u64 v[34:35], v[20:21], 0, v[34:35]
	global_load_dword v64, v[36:37], off
	global_load_dword v65, v[34:35], off
	v_or_b32_e32 v25, s12, v1
	v_or_b32_e32 v26, s13, v0
	v_mad_u64_u32 v[66:67], s[18:19], v26, s16, v[2:3]
	v_mad_u64_u32 v[68:69], s[18:19], v25, s16, v[2:3]
	s_add_i32 s19, s13, 4
	s_add_i32 s18, s12, 4
	v_or_b32_e32 v128, s19, v22
	v_mov_b32_e32 v35, v129
	v_or_b32_e32 v25, s18, v1
	v_or_b32_e32 v26, s19, v0
	s_add_i32 s9, s9, 16
	s_add_i32 s8, s8, 16
	s_add_i32 s15, s15, -16
	v_or_b32_e32 v34, s18, v3
	v_lshlrev_b64 v[36:37], 12, v[128:129]
	v_lshlrev_b64 v[34:35], 12, v[34:35]
	v_lshl_add_u64 v[36:37], v[20:21], 0, v[36:37]
	v_lshl_add_u64 v[34:35], v[20:21], 0, v[34:35]
	global_load_dword v70, v[36:37], off
	global_load_dword v71, v[34:35], off
	v_mad_u64_u32 v[72:73], s[18:19], v26, s16, v[2:3]
	v_mad_u64_u32 v[74:75], s[18:19], v25, s16, v[2:3]
	s_add_i32 s19, s13, 8
	s_add_i32 s18, s12, 8
	v_or_b32_e32 v128, s19, v22
	v_mov_b32_e32 v35, v129
	v_or_b32_e32 v25, s18, v1
	v_or_b32_e32 v26, s19, v0
	v_or_b32_e32 v34, s18, v3
	v_lshlrev_b64 v[36:37], 12, v[128:129]
	v_lshlrev_b64 v[34:35], 12, v[34:35]
	v_lshl_add_u64 v[36:37], v[20:21], 0, v[36:37]
	v_lshl_add_u64 v[34:35], v[20:21], 0, v[34:35]
	global_load_dword v76, v[36:37], off
	global_load_dword v77, v[34:35], off
	v_mad_u64_u32 v[78:79], s[18:19], v26, s16, v[2:3]
	v_mad_u64_u32 v[80:81], s[18:19], v25, s16, v[2:3]
	s_add_i32 s19, s13, 12
	s_add_i32 s18, s12, 12
	v_or_b32_e32 v128, s19, v22
	v_mov_b32_e32 v35, v129
	v_or_b32_e32 v25, s18, v1
	v_or_b32_e32 v26, s19, v0
	v_or_b32_e32 v34, s18, v3
	v_lshlrev_b64 v[36:37], 12, v[128:129]
	v_lshlrev_b64 v[34:35], 12, v[34:35]
	v_lshl_add_u64 v[36:37], v[20:21], 0, v[36:37]
	v_lshl_add_u64 v[34:35], v[20:21], 0, v[34:35]
	global_load_dword v82, v[36:37], off
	global_load_dword v83, v[34:35], off
	v_mad_u64_u32 v[84:85], s[18:19], v26, s16, v[2:3]
	v_mad_u64_u32 v[86:87], s[18:19], v25, s16, v[2:3]
	s_add_i32 s19, s13, 16
	s_add_i32 s18, s12, 16
	v_or_b32_e32 v128, s19, v22
	v_mov_b32_e32 v35, v129
	v_or_b32_e32 v25, s18, v1
	v_or_b32_e32 v26, s19, v0
	v_or_b32_e32 v34, s18, v3
	v_lshlrev_b64 v[36:37], 12, v[128:129]
	v_lshlrev_b64 v[34:35], 12, v[34:35]
	v_lshl_add_u64 v[36:37], v[20:21], 0, v[36:37]
	v_lshl_add_u64 v[34:35], v[20:21], 0, v[34:35]
	global_load_dword v88, v[36:37], off
	global_load_dword v89, v[34:35], off
	v_mad_u64_u32 v[90:91], s[18:19], v26, s16, v[2:3]
	v_mad_u64_u32 v[92:93], s[18:19], v25, s16, v[2:3]
	s_add_i32 s19, s13, 20
	s_add_i32 s18, s12, 20
	v_or_b32_e32 v128, s19, v22
	v_mov_b32_e32 v35, v129
	v_or_b32_e32 v25, s18, v1
	v_or_b32_e32 v26, s19, v0
	v_or_b32_e32 v34, s18, v3
	v_lshlrev_b64 v[36:37], 12, v[128:129]
	v_lshlrev_b64 v[34:35], 12, v[34:35]
	v_lshl_add_u64 v[36:37], v[20:21], 0, v[36:37]
	v_lshl_add_u64 v[34:35], v[20:21], 0, v[34:35]
	global_load_dword v94, v[36:37], off
	global_load_dword v95, v[34:35], off
	v_mad_u64_u32 v[96:97], s[18:19], v26, s16, v[2:3]
	v_mad_u64_u32 v[98:99], s[18:19], v25, s16, v[2:3]
	s_add_i32 s19, s13, 24
	s_add_i32 s18, s12, 24
	v_or_b32_e32 v128, s19, v22
	v_mov_b32_e32 v35, v129
	v_or_b32_e32 v25, s18, v1
	v_or_b32_e32 v26, s19, v0
	s_add_i32 s13, s13, 28
	s_add_i32 s12, s12, 28
	s_cmp_lg_u32 s15, 0
	v_or_b32_e32 v34, s18, v3
	v_lshlrev_b64 v[36:37], 12, v[128:129]
	v_lshlrev_b64 v[34:35], 12, v[34:35]
	v_lshl_add_u64 v[36:37], v[20:21], 0, v[36:37]
	v_lshl_add_u64 v[34:35], v[20:21], 0, v[34:35]
	global_load_dword v100, v[36:37], off
	global_load_dword v101, v[34:35], off
	v_mad_u64_u32 v[102:103], s[18:19], v26, s16, v[2:3]
	v_mad_u64_u32 v[104:105], s[18:19], v25, s16, v[2:3]
	v_or_b32_e32 v128, s13, v22
	v_mov_b32_e32 v35, v129
	v_or_b32_e32 v26, s13, v0
	v_or_b32_e32 v25, s12, v1
	v_or_b32_e32 v34, s12, v3
	v_lshlrev_b64 v[36:37], 12, v[128:129]
	v_lshlrev_b64 v[34:35], 12, v[34:35]
	v_lshl_add_u64 v[36:37], v[20:21], 0, v[36:37]
	v_lshl_add_u64 v[34:35], v[20:21], 0, v[34:35]
	global_load_dword v106, v[36:37], off
	global_load_dword v107, v[34:35], off
	v_mad_u64_u32 v[108:109], s[12:13], v26, s16, v[2:3]
	v_mad_u64_u32 v[110:111], s[12:13], v25, s16, v[2:3]
	s_waitcnt vmcnt(15)
	ds_write_b32 v66, v64
	s_waitcnt vmcnt(14)
	ds_write_b32 v68, v65
	s_waitcnt vmcnt(13)
	ds_write_b32 v72, v70
	s_waitcnt vmcnt(12)
	ds_write_b32 v74, v71
	s_waitcnt vmcnt(11)
	ds_write_b32 v78, v76
	s_waitcnt vmcnt(10)
	ds_write_b32 v80, v77
	s_waitcnt vmcnt(9)
	ds_write_b32 v84, v82
	s_waitcnt vmcnt(8)
	ds_write_b32 v86, v83
	s_waitcnt vmcnt(7)
	ds_write_b32 v90, v88
	s_waitcnt vmcnt(6)
	ds_write_b32 v92, v89
	s_waitcnt vmcnt(5)
	ds_write_b32 v96, v94
	s_waitcnt vmcnt(4)
	ds_write_b32 v98, v95
	s_waitcnt vmcnt(3)
	ds_write_b32 v102, v100
	s_waitcnt vmcnt(2)
	ds_write_b32 v104, v101
	s_waitcnt vmcnt(1)
	ds_write_b32 v108, v106
	s_waitcnt vmcnt(0)
	ds_write_b32 v110, v107
	s_cbranch_scc1 .LBB0_96
; __device__ __forceinline__ unsigned pk2(float lo, float hi) { f32x2_t v = {lo, hi}; bf16x2_t b = __builtin_convertvector(v, bf16x2_t); return __builtin_bit_cast(unsigned, b); }
; __device__ __forceinline__ void transpose_item(const float* W, int K, int N, bf16_t* WT, int mode, float* scr, int item, int lane) {
;     ...
;     asm volatile("s_waitcnt lgkmcnt(0)" ::: "memory");
;     const int c = lane & 7;
; #pragma unroll
;     for (int j = 0; j < 4; ++j) { const int n = (lane >> 3) + 8 * j; const float* s = scr + (8 * c) * 33 + n;
;         u32x4 o; o.x = pk2(s[0 * 33], s[1 * 33]); o.y = pk2(s[2 * 33], s[3 * 33]); o.z = pk2(s[4 * 33], s[5 * 33]); o.w = pk2(s[6 * 33], s[7 * 33]);
;         *(u32x4*)(WT + (size_t)(r0 + n) * K + k0 + 8 * c) = o; }
;     asm volatile("s_waitcnt lgkmcnt(0)" ::: "memory");
	s_waitcnt lgkmcnt(0)
	v_lshlrev_b32_e32 v128, 1, v24
	ds_read2_b32 v[20:21], v29 offset0:33 offset1:41
	ds_read2_b32 v[24:25], v29 offset1:8
	ds_read2_b32 v[38:39], v29 offset0:66 offset1:74
	ds_read2_b32 v[40:41], v29 offset0:99 offset1:107
	ds_read2_b32 v[42:43], v29 offset0:132 offset1:140
	ds_read2_b32 v[44:45], v29 offset0:165 offset1:173
	ds_read2_b32 v[46:47], v29 offset0:198 offset1:206
	ds_read2_b32 v[48:49], v29 offset0:231 offset1:239
	v_or_b32_e32 v3, v23, v28
	v_lshl_add_u64 v[50:51], v[8:9], 0, v[128:129]
	v_lshlrev_b32_e32 v128, 11, v3
	s_waitcnt lgkmcnt(6)
	v_cvt_pk_bf16_f32 v34, v24, v20
	s_waitcnt lgkmcnt(4)
	v_cvt_pk_bf16_f32 v35, v38, v40
	s_waitcnt lgkmcnt(2)
	v_cvt_pk_bf16_f32 v36, v42, v44
	s_waitcnt lgkmcnt(0)
	v_cvt_pk_bf16_f32 v37, v46, v48
	v_lshl_add_u64 v[52:53], v[50:51], 0, v[128:129]
	global_store_dwordx4 v[52:53], v[34:37], off
	v_or_b32_e32 v3, v23, v30
	v_lshlrev_b32_e32 v128, 11, v3
	v_cvt_pk_bf16_f32 v34, v25, v21
	v_cvt_pk_bf16_f32 v35, v39, v41
	v_cvt_pk_bf16_f32 v36, v43, v45
	v_cvt_pk_bf16_f32 v37, v47, v49
	ds_read2_b32 v[24:25], v29 offset0:49 offset1:57
	ds_read2_b32 v[38:39], v29 offset0:16 offset1:24
	ds_read2_b32 v[40:41], v29 offset0:82 offset1:90
	ds_read2_b32 v[42:43], v29 offset0:115 offset1:123
	ds_read2_b32 v[44:45], v29 offset0:148 offset1:156
	ds_read2_b32 v[46:47], v29 offset0:181 offset1:189
	ds_read2_b32 v[48:49], v29 offset0:214 offset1:222
	ds_read2_b32 v[52:53], v29 offset0:247 offset1:255
	v_or_b32_e32 v3, v23, v31
	v_lshl_add_u64 v[20:21], v[50:51], 0, v[128:129]
	v_lshlrev_b32_e32 v128, 11, v3
	v_or_b32_e32 v3, v23, v32
	global_store_dwordx4 v[20:21], v[34:37], off
	v_lshl_add_u64 v[20:21], v[50:51], 0, v[128:129]
	v_lshlrev_b32_e32 v128, 11, v3
	s_waitcnt lgkmcnt(6)
	v_cvt_pk_bf16_f32 v34, v38, v24
	s_waitcnt lgkmcnt(4)
	v_cvt_pk_bf16_f32 v35, v40, v42
	s_waitcnt lgkmcnt(2)
	v_cvt_pk_bf16_f32 v36, v44, v46
	s_waitcnt lgkmcnt(0)
	v_cvt_pk_bf16_f32 v37, v48, v52
	global_store_dwordx4 v[20:21], v[34:37], off
	v_lshl_add_u64 v[20:21], v[50:51], 0, v[128:129]
	s_nop 0
	v_cvt_pk_bf16_f32 v34, v39, v25
	v_cvt_pk_bf16_f32 v35, v41, v43
	v_cvt_pk_bf16_f32 v36, v45, v47
	v_cvt_pk_bf16_f32 v37, v49, v53
	global_store_dwordx4 v[20:21], v[34:37], off
	s_waitcnt lgkmcnt(0)

; __device__ __forceinline__ unsigned pk2(float lo, float hi) { f32x2_t v = {lo, hi}; bf16x2_t b = __builtin_convertvector(v, bf16x2_t); return __builtin_bit_cast(unsigned, b); }
; __device__ __forceinline__ void transpose_item(const float* W, int K, int N, bf16_t* WT, int mode, float* scr, int item, int lane) {
;     const int nblk = N / 32, kb = item / nblk, nb = item % nblk, k0 = 64 * kb, n0 = 32 * nb;
;     int r0 = n0;
;     if (mode == 1) { r0 = (n0 < FFH) ? (n0 / 128) * 256 + (n0 % 128) : ((n0 - FFH) / 128) * 256 + 128 + ((n0 - FFH) % 128); }
; #pragma unroll 8
;     for (int i = 0; i < 32; ++i) { const int kk = 2 * i + (lane >> 5); scr[kk * 33 + (lane & 31)] = W[(size_t)(k0 + kk) * N + n0 + (lane & 31)]; }
;     asm volatile("s_waitcnt lgkmcnt(0)" ::: "memory");
;     const int c = lane & 7;
; #pragma unroll
;     for (int j = 0; j < 4; ++j) { const int n = (lane >> 3) + 8 * j; const float* s = scr + (8 * c) * 33 + n;
;         u32x4 o; o.x = pk2(s[0 * 33], s[1 * 33]); o.y = pk2(s[2 * 33], s[3 * 33]); o.z = pk2(s[4 * 33], s[5 * 33]); o.w = pk2(s[6 * 33], s[7 * 33]);
;         *(u32x4*)(WT + (size_t)(r0 + n) * K + k0 + 8 * c) = o; }
;     asm volatile("s_waitcnt lgkmcnt(0)" ::: "memory");
.LBB0_101:
	s_lshl_b32 s15, s9, 1
	s_lshl_b32 s13, s8, 1
	v_or_b32_e32 v34, s15, v26
	v_or_b32_e32 v33, s13, v3
	v_mad_i64_i32 v[34:35], s[18:19], v34, s22, v[24:25]
	v_mad_i64_i32 v[36:37], s[18:19], v33, s22, v[24:25]
	global_load_dword v64, v[34:35], off
	global_load_dword v65, v[36:37], off
	v_or_b32_e32 v21, s13, v1
	v_or_b32_e32 v23, s15, v0
	v_mad_u64_u32 v[66:67], s[18:19], v23, s16, v[2:3]
	v_mad_u64_u32 v[68:69], s[18:19], v21, s16, v[2:3]
	s_add_i32 s19, s15, 4
	s_add_i32 s18, s13, 4
	v_or_b32_e32 v21, s18, v1
	v_or_b32_e32 v23, s19, v0
	s_add_i32 s9, s9, 16
	s_add_i32 s8, s8, 16
	s_add_i32 s12, s12, -16
	v_or_b32_e32 v34, s19, v26
	v_or_b32_e32 v33, s18, v3
	v_mad_i64_i32 v[34:35], s[18:19], v34, s22, v[24:25]
	v_mad_i64_i32 v[36:37], s[18:19], v33, s22, v[24:25]
	global_load_dword v70, v[34:35], off
	global_load_dword v71, v[36:37], off
	v_mad_u64_u32 v[72:73], s[18:19], v23, s16, v[2:3]
	v_mad_u64_u32 v[74:75], s[18:19], v21, s16, v[2:3]
	s_add_i32 s19, s15, 8
	s_add_i32 s18, s13, 8
	v_or_b32_e32 v21, s18, v1
	v_or_b32_e32 v23, s19, v0
	v_or_b32_e32 v34, s19, v26
	v_or_b32_e32 v33, s18, v3
	v_mad_i64_i32 v[34:35], s[18:19], v34, s22, v[24:25]
	v_mad_i64_i32 v[36:37], s[18:19], v33, s22, v[24:25]
	global_load_dword v76, v[34:35], off
	global_load_dword v77, v[36:37], off
	v_mad_u64_u32 v[78:79], s[18:19], v23, s16, v[2:3]
	v_mad_u64_u32 v[80:81], s[18:19], v21, s16, v[2:3]
	s_add_i32 s19, s15, 12
	s_add_i32 s18, s13, 12
	v_or_b32_e32 v21, s18, v1
	v_or_b32_e32 v23, s19, v0
	v_or_b32_e32 v34, s19, v26
	v_or_b32_e32 v33, s18, v3
	v_mad_i64_i32 v[34:35], s[18:19], v34, s22, v[24:25]
	v_mad_i64_i32 v[36:37], s[18:19], v33, s22, v[24:25]
	global_load_dword v82, v[34:35], off
	global_load_dword v83, v[36:37], off
	v_mad_u64_u32 v[84:85], s[18:19], v23, s16, v[2:3]
	v_mad_u64_u32 v[86:87], s[18:19], v21, s16, v[2:3]
	s_add_i32 s19, s15, 16
	s_add_i32 s18, s13, 16
	v_or_b32_e32 v21, s18, v1
	v_or_b32_e32 v23, s19, v0
	v_or_b32_e32 v34, s19, v26
	v_or_b32_e32 v33, s18, v3
	v_mad_i64_i32 v[34:35], s[18:19], v34, s22, v[24:25]
	v_mad_i64_i32 v[36:37], s[18:19], v33, s22, v[24:25]
	global_load_dword v88, v[34:35], off
	global_load_dword v89, v[36:37], off
	v_mad_u64_u32 v[90:91], s[18:19], v23, s16, v[2:3]
	v_mad_u64_u32 v[92:93], s[18:19], v21, s16, v[2:3]
	s_add_i32 s19, s15, 20
	s_add_i32 s18, s13, 20
	v_or_b32_e32 v21, s18, v1
	v_or_b32_e32 v23, s19, v0
	v_or_b32_e32 v34, s19, v26
	v_or_b32_e32 v33, s18, v3
	v_mad_i64_i32 v[34:35], s[18:19], v34, s22, v[24:25]
	v_mad_i64_i32 v[36:37], s[18:19], v33, s22, v[24:25]
	global_load_dword v94, v[34:35], off
	global_load_dword v95, v[36:37], off
	v_mad_u64_u32 v[96:97], s[18:19], v23, s16, v[2:3]
	v_mad_u64_u32 v[98:99], s[18:19], v21, s16, v[2:3]
	s_add_i32 s19, s15, 24
	s_add_i32 s18, s13, 24
	v_or_b32_e32 v21, s18, v1
	v_or_b32_e32 v23, s19, v0
	s_add_i32 s15, s15, 28
	s_add_i32 s13, s13, 28
	s_cmp_lg_u32 s12, 0
	v_or_b32_e32 v34, s19, v26
	v_or_b32_e32 v33, s18, v3
	v_mad_i64_i32 v[34:35], s[18:19], v34, s22, v[24:25]
	v_mad_i64_i32 v[36:37], s[18:19], v33, s22, v[24:25]
	global_load_dword v100, v[34:35], off
	global_load_dword v101, v[36:37], off
	v_mad_u64_u32 v[102:103], s[18:19], v23, s16, v[2:3]
	v_mad_u64_u32 v[104:105], s[18:19], v21, s16, v[2:3]
	v_or_b32_e32 v23, s15, v0
	v_or_b32_e32 v21, s13, v1
	v_or_b32_e32 v34, s15, v26
	v_or_b32_e32 v33, s13, v3
	v_mad_i64_i32 v[34:35], s[18:19], v34, s22, v[24:25]
	v_mad_i64_i32 v[36:37], s[18:19], v33, s22, v[24:25]
	global_load_dword v106, v[34:35], off
	global_load_dword v107, v[36:37], off
	v_mad_u64_u32 v[108:109], s[18:19], v23, s16, v[2:3]
	v_mad_u64_u32 v[110:111], s[18:19], v21, s16, v[2:3]
	s_waitcnt vmcnt(15)
	ds_write_b32 v66, v64
	s_waitcnt vmcnt(14)
	ds_write_b32 v68, v65
	s_waitcnt vmcnt(13)
	ds_write_b32 v72, v70
	s_waitcnt vmcnt(12)
	ds_write_b32 v74, v71
	s_waitcnt vmcnt(11)
	ds_write_b32 v78, v76
	s_waitcnt vmcnt(10)
	ds_write_b32 v80, v77
	s_waitcnt vmcnt(9)
	ds_write_b32 v84, v82
	s_waitcnt vmcnt(8)
	ds_write_b32 v86, v83
	s_waitcnt vmcnt(7)
	ds_write_b32 v90, v88
	s_waitcnt vmcnt(6)
	ds_write_b32 v92, v89
	s_waitcnt vmcnt(5)
	ds_write_b32 v96, v94
	s_waitcnt vmcnt(4)
	ds_write_b32 v98, v95
	s_waitcnt vmcnt(3)
	ds_write_b32 v102, v100
	s_waitcnt vmcnt(2)
	ds_write_b32 v104, v101
	s_waitcnt vmcnt(1)
	ds_write_b32 v108, v106
	s_waitcnt vmcnt(0)
	ds_write_b32 v110, v107
	s_cbranch_scc1 .LBB0_101
	s_waitcnt lgkmcnt(0)
	ds_read2_b32 v[34:35], v29 offset0:33 offset1:41
	ds_read2_b32 v[36:37], v29 offset1:8
	ds_read2_b32 v[38:39], v29 offset0:66 offset1:74
	ds_read2_b32 v[40:41], v29 offset0:99 offset1:107
	ds_read2_b32 v[42:43], v29 offset0:132 offset1:140
	ds_read2_b32 v[44:45], v29 offset0:165 offset1:173
	ds_read2_b32 v[46:47], v29 offset0:198 offset1:206
	ds_read2_b32 v[48:49], v29 offset0:231 offset1:239
	v_or_b32_e32 v52, v20, v28
	v_ashrrev_i32_e32 v23, 31, v22
	v_ashrrev_i32_e32 v53, 31, v52
	v_lshl_add_u64 v[50:51], v[22:23], 1, v[10:11]
	v_lshlrev_b64 v[52:53], 11, v[52:53]
	s_waitcnt lgkmcnt(6)
	v_cvt_pk_bf16_f32 v22, v36, v34
	s_waitcnt lgkmcnt(4)
	v_cvt_pk_bf16_f32 v23, v38, v40
	s_waitcnt lgkmcnt(2)
	v_cvt_pk_bf16_f32 v24, v42, v44
	s_waitcnt lgkmcnt(0)
	v_cvt_pk_bf16_f32 v25, v46, v48
	v_lshl_add_u64 v[52:53], v[50:51], 0, v[52:53]
	v_or_b32_e32 v34, v20, v30
	global_store_dwordx4 v[52:53], v[22:25], off
	s_nop 1
	v_cvt_pk_bf16_f32 v22, v37, v35
	v_ashrrev_i32_e32 v35, 31, v34
	v_cvt_pk_bf16_f32 v23, v39, v41
	v_cvt_pk_bf16_f32 v24, v43, v45
	v_cvt_pk_bf16_f32 v25, v47, v49
	v_lshlrev_b64 v[34:35], 11, v[34:35]
	ds_read2_b32 v[36:37], v29 offset0:49 offset1:57
	ds_read2_b32 v[38:39], v29 offset0:16 offset1:24
	ds_read2_b32 v[40:41], v29 offset0:82 offset1:90
	ds_read2_b32 v[42:43], v29 offset0:115 offset1:123
	ds_read2_b32 v[44:45], v29 offset0:148 offset1:156
	ds_read2_b32 v[46:47], v29 offset0:181 offset1:189
	ds_read2_b32 v[48:49], v29 offset0:214 offset1:222
	ds_read2_b32 v[52:53], v29 offset0:247 offset1:255
	v_lshl_add_u64 v[34:35], v[50:51], 0, v[34:35]
	global_store_dwordx4 v[34:35], v[22:25], off
	v_or_b32_e32 v34, v20, v31
	v_ashrrev_i32_e32 v35, 31, v34
	v_or_b32_e32 v20, v20, v32
	v_lshlrev_b64 v[34:35], 11, v[34:35]
	v_ashrrev_i32_e32 v21, 31, v20
	s_waitcnt lgkmcnt(6)
	v_cvt_pk_bf16_f32 v22, v38, v36
	s_waitcnt lgkmcnt(4)
	v_cvt_pk_bf16_f32 v23, v40, v42
	s_waitcnt lgkmcnt(2)
	v_cvt_pk_bf16_f32 v24, v44, v46
	s_waitcnt lgkmcnt(0)
	v_cvt_pk_bf16_f32 v25, v48, v52
	v_lshl_add_u64 v[34:35], v[50:51], 0, v[34:35]
	v_lshlrev_b64 v[20:21], 11, v[20:21]
	global_store_dwordx4 v[34:35], v[22:25], off
	v_lshl_add_u64 v[20:21], v[50:51], 0, v[20:21]
	s_nop 0
	v_cvt_pk_bf16_f32 v22, v39, v37
	v_cvt_pk_bf16_f32 v23, v41, v43
	v_cvt_pk_bf16_f32 v24, v45, v47
	v_cvt_pk_bf16_f32 v25, v49, v53
	global_store_dwordx4 v[20:21], v[22:25], off
	s_waitcnt lgkmcnt(0)
	s_branch .LBB0_79

; __device__ __forceinline__ void transpose_item(const float* W, int K, int N, bf16_t* WT, int mode, float* scr, int item, int lane) {
;     const int nblk = N / 32, kb = item / nblk, nb = item % nblk, k0 = 64 * kb, n0 = 32 * nb;
;     int r0 = n0;
;     if (mode == 1) { r0 = (n0 < FFH) ? (n0 / 128) * 256 + (n0 % 128) : ((n0 - FFH) / 128) * 256 + 128 + ((n0 - FFH) % 128); }
; #pragma unroll 8
;     for (int i = 0; i < 32; ++i) { const int kk = 2 * i + (lane >> 5); scr[kk * 33 + (lane & 31)] = W[(size_t)(k0 + kk) * N + n0 + (lane & 31)]; }
.LBB0_1143:
	s_lshl_b32 s13, s9, 1
	s_lshl_b32 s12, s8, 1
	v_or_b32_e32 v128, s13, v22
	v_or_b32_e32 v34, s12, v3
	v_mov_b32_e32 v35, v129
	v_lshlrev_b64 v[36:37], 12, v[128:129]
	v_lshlrev_b64 v[34:35], 12, v[34:35]
	v_lshl_add_u64 v[36:37], v[20:21], 0, v[36:37]
	v_lshl_add_u64 v[34:35], v[20:21], 0, v[34:35]
	global_load_dword v64, v[36:37], off
	global_load_dword v65, v[34:35], off
	v_or_b32_e32 v25, s12, v1
	v_or_b32_e32 v26, s13, v0
	v_mad_u64_u32 v[66:67], s[18:19], v26, s16, v[2:3]
	v_mad_u64_u32 v[68:69], s[18:19], v25, s16, v[2:3]
	s_add_i32 s19, s13, 4
	s_add_i32 s18, s12, 4
	v_or_b32_e32 v128, s19, v22
	v_mov_b32_e32 v35, v129
	v_or_b32_e32 v25, s18, v1
	v_or_b32_e32 v26, s19, v0
	s_add_i32 s9, s9, 16
	s_add_i32 s8, s8, 16
	s_add_i32 s15, s15, -16
	v_or_b32_e32 v34, s18, v3
	v_lshlrev_b64 v[36:37], 12, v[128:129]
	v_lshlrev_b64 v[34:35], 12, v[34:35]
	v_lshl_add_u64 v[36:37], v[20:21], 0, v[36:37]
	v_lshl_add_u64 v[34:35], v[20:21], 0, v[34:35]
	global_load_dword v70, v[36:37], off
	global_load_dword v71, v[34:35], off
	v_mad_u64_u32 v[72:73], s[18:19], v26, s16, v[2:3]
	v_mad_u64_u32 v[74:75], s[18:19], v25, s16, v[2:3]
	s_add_i32 s19, s13, 8
	s_add_i32 s18, s12, 8
	v_or_b32_e32 v128, s19, v22
	v_mov_b32_e32 v35, v129
	v_or_b32_e32 v25, s18, v1
	v_or_b32_e32 v26, s19, v0
	v_or_b32_e32 v34, s18, v3
	v_lshlrev_b64 v[36:37], 12, v[128:129]
	v_lshlrev_b64 v[34:35], 12, v[34:35]
	v_lshl_add_u64 v[36:37], v[20:21], 0, v[36:37]
	v_lshl_add_u64 v[34:35], v[20:21], 0, v[34:35]
	global_load_dword v76, v[36:37], off
	global_load_dword v77, v[34:35], off
	v_mad_u64_u32 v[78:79], s[18:19], v26, s16, v[2:3]
	v_mad_u64_u32 v[80:81], s[18:19], v25, s16, v[2:3]
	s_add_i32 s19, s13, 12
	s_add_i32 s18, s12, 12
	v_or_b32_e32 v128, s19, v22
	v_mov_b32_e32 v35, v129
	v_or_b32_e32 v25, s18, v1
	v_or_b32_e32 v26, s19, v0
	v_or_b32_e32 v34, s18, v3
	v_lshlrev_b64 v[36:37], 12, v[128:129]
	v_lshlrev_b64 v[34:35], 12, v[34:35]
	v_lshl_add_u64 v[36:37], v[20:21], 0, v[36:37]
	v_lshl_add_u64 v[34:35], v[20:21], 0, v[34:35]
	global_load_dword v82, v[36:37], off
	global_load_dword v83, v[34:35], off
	v_mad_u64_u32 v[84:85], s[18:19], v26, s16, v[2:3]
	v_mad_u64_u32 v[86:87], s[18:19], v25, s16, v[2:3]
	s_add_i32 s19, s13, 16
	s_add_i32 s18, s12, 16
	v_or_b32_e32 v128, s19, v22
	v_mov_b32_e32 v35, v129
	v_or_b32_e32 v25, s18, v1
	v_or_b32_e32 v26, s19, v0
	v_or_b32_e32 v34, s18, v3
	v_lshlrev_b64 v[36:37], 12, v[128:129]
	v_lshlrev_b64 v[34:35], 12, v[34:35]
	v_lshl_add_u64 v[36:37], v[20:21], 0, v[36:37]
	v_lshl_add_u64 v[34:35], v[20:21], 0, v[34:35]
	global_load_dword v88, v[36:37], off
	global_load_dword v89, v[34:35], off
	v_mad_u64_u32 v[90:91], s[18:19], v26, s16, v[2:3]
	v_mad_u64_u32 v[92:93], s[18:19], v25, s16, v[2:3]
	s_add_i32 s19, s13, 20
	s_add_i32 s18, s12, 20
	v_or_b32_e32 v128, s19, v22
	v_mov_b32_e32 v35, v129
	v_or_b32_e32 v25, s18, v1
	v_or_b32_e32 v26, s19, v0
	v_or_b32_e32 v34, s18, v3
	v_lshlrev_b64 v[36:37], 12, v[128:129]
	v_lshlrev_b64 v[34:35], 12, v[34:35]
	v_lshl_add_u64 v[36:37], v[20:21], 0, v[36:37]
	v_lshl_add_u64 v[34:35], v[20:21], 0, v[34:35]
	global_load_dword v94, v[36:37], off
	global_load_dword v95, v[34:35], off
	v_mad_u64_u32 v[96:97], s[18:19], v26, s16, v[2:3]
	v_mad_u64_u32 v[98:99], s[18:19], v25, s16, v[2:3]
	s_add_i32 s19, s13, 24
	s_add_i32 s18, s12, 24
	v_or_b32_e32 v128, s19, v22
	v_mov_b32_e32 v35, v129
	v_or_b32_e32 v25, s18, v1
	v_or_b32_e32 v26, s19, v0
	s_add_i32 s13, s13, 28
	s_add_i32 s12, s12, 28
	s_cmp_lg_u32 s15, 0
	v_or_b32_e32 v34, s18, v3
	v_lshlrev_b64 v[36:37], 12, v[128:129]
	v_lshlrev_b64 v[34:35], 12, v[34:35]
	v_lshl_add_u64 v[36:37], v[20:21], 0, v[36:37]
	v_lshl_add_u64 v[34:35], v[20:21], 0, v[34:35]
	global_load_dword v100, v[36:37], off
	global_load_dword v101, v[34:35], off
	v_mad_u64_u32 v[102:103], s[18:19], v26, s16, v[2:3]
	v_mad_u64_u32 v[104:105], s[18:19], v25, s16, v[2:3]
	v_or_b32_e32 v128, s13, v22
	v_mov_b32_e32 v35, v129
	v_or_b32_e32 v26, s13, v0
	v_or_b32_e32 v25, s12, v1
	v_or_b32_e32 v34, s12, v3
	v_lshlrev_b64 v[36:37], 12, v[128:129]
	v_lshlrev_b64 v[34:35], 12, v[34:35]
	v_lshl_add_u64 v[36:37], v[20:21], 0, v[36:37]
	v_lshl_add_u64 v[34:35], v[20:21], 0, v[34:35]
	global_load_dword v106, v[36:37], off
	global_load_dword v107, v[34:35], off
	v_mad_u64_u32 v[108:109], s[12:13], v26, s16, v[2:3]
	v_mad_u64_u32 v[110:111], s[12:13], v25, s16, v[2:3]
	s_waitcnt vmcnt(15)
	ds_write_b32 v66, v64
	s_waitcnt vmcnt(14)
	ds_write_b32 v68, v65
	s_waitcnt vmcnt(13)
	ds_write_b32 v72, v70
	s_waitcnt vmcnt(12)
	ds_write_b32 v74, v71
	s_waitcnt vmcnt(11)
	ds_write_b32 v78, v76
	s_waitcnt vmcnt(10)
	ds_write_b32 v80, v77
	s_waitcnt vmcnt(9)
	ds_write_b32 v84, v82
	s_waitcnt vmcnt(8)
	ds_write_b32 v86, v83
	s_waitcnt vmcnt(7)
	ds_write_b32 v90, v88
	s_waitcnt vmcnt(6)
	ds_write_b32 v92, v89
	s_waitcnt vmcnt(5)
	ds_write_b32 v96, v94
	s_waitcnt vmcnt(4)
	ds_write_b32 v98, v95
	s_waitcnt vmcnt(3)
	ds_write_b32 v102, v100
	s_waitcnt vmcnt(2)
	ds_write_b32 v104, v101
	s_waitcnt vmcnt(1)
	ds_write_b32 v108, v106
	s_waitcnt vmcnt(0)
	ds_write_b32 v110, v107
	s_cbranch_scc1 .LBB0_1143
; __device__ __forceinline__ unsigned pk2(float lo, float hi) { f32x2_t v = {lo, hi}; bf16x2_t b = __builtin_convertvector(v, bf16x2_t); return __builtin_bit_cast(unsigned, b); }
; __device__ __forceinline__ void transpose_item(const float* W, int K, int N, bf16_t* WT, int mode, float* scr, int item, int lane) {
;     ...
;     asm volatile("s_waitcnt lgkmcnt(0)" ::: "memory");
;     const int c = lane & 7;
; #pragma unroll
;     for (int j = 0; j < 4; ++j) { const int n = (lane >> 3) + 8 * j; const float* s = scr + (8 * c) * 33 + n;
;         u32x4 o; o.x = pk2(s[0 * 33], s[1 * 33]); o.y = pk2(s[2 * 33], s[3 * 33]); o.z = pk2(s[4 * 33], s[5 * 33]); o.w = pk2(s[6 * 33], s[7 * 33]);
;         *(u32x4*)(WT + (size_t)(r0 + n) * K + k0 + 8 * c) = o; }
;     asm volatile("s_waitcnt lgkmcnt(0)" ::: "memory");
	s_waitcnt lgkmcnt(0)
	v_lshlrev_b32_e32 v128, 1, v24
	ds_read2_b32 v[24:25], v29 offset0:33 offset1:41
	ds_read2_b32 v[38:39], v29 offset1:8
	ds_read2_b32 v[40:41], v29 offset0:66 offset1:74
	ds_read2_b32 v[42:43], v29 offset0:99 offset1:107
	ds_read2_b32 v[44:45], v29 offset0:132 offset1:140
	ds_read2_b32 v[46:47], v29 offset0:165 offset1:173
	ds_read2_b32 v[48:49], v29 offset0:198 offset1:206
	ds_read2_b32 v[50:51], v29 offset0:231 offset1:239
	v_or_b32_e32 v3, v23, v28
	v_mul_u32_u24_e32 v3, 0xb00, v3
	v_lshl_add_u64 v[20:21], v[4:5], 0, v[128:129]
	v_lshlrev_b32_e32 v128, 1, v3
	v_or_b32_e32 v3, v23, v30
	v_mul_u32_u24_e32 v3, 0xb00, v3
	s_waitcnt lgkmcnt(6)
	v_cvt_pk_bf16_f32 v34, v38, v24
	s_waitcnt lgkmcnt(4)
	v_cvt_pk_bf16_f32 v35, v40, v42
	s_waitcnt lgkmcnt(2)
	v_cvt_pk_bf16_f32 v36, v44, v46
	s_waitcnt lgkmcnt(0)
	v_cvt_pk_bf16_f32 v37, v48, v50
	v_lshl_add_u64 v[52:53], v[20:21], 0, v[128:129]
	v_lshlrev_b32_e32 v128, 1, v3
	global_store_dwordx4 v[52:53], v[34:37], off
	v_or_b32_e32 v3, v23, v31
	v_mul_u32_u24_e32 v3, 0xb00, v3
	v_cvt_pk_bf16_f32 v34, v39, v25
	v_cvt_pk_bf16_f32 v35, v41, v43
	v_cvt_pk_bf16_f32 v36, v45, v47
	v_cvt_pk_bf16_f32 v37, v49, v51
	v_lshl_add_u64 v[24:25], v[20:21], 0, v[128:129]
	global_store_dwordx4 v[24:25], v[34:37], off
	ds_read2_b32 v[24:25], v29 offset0:16 offset1:24
	ds_read2_b32 v[38:39], v29 offset0:49 offset1:57
	ds_read2_b32 v[40:41], v29 offset0:82 offset1:90
	ds_read2_b32 v[42:43], v29 offset0:115 offset1:123
	ds_read2_b32 v[44:45], v29 offset0:148 offset1:156
	ds_read2_b32 v[46:47], v29 offset0:181 offset1:189
	ds_read2_b32 v[48:49], v29 offset0:214 offset1:222
	ds_read2_b32 v[50:51], v29 offset0:247 offset1:255
	v_lshlrev_b32_e32 v128, 1, v3
	v_or_b32_e32 v3, v23, v32
	v_mul_u32_u24_e32 v3, 0xb00, v3
	s_waitcnt lgkmcnt(6)
	v_cvt_pk_bf16_f32 v34, v24, v38
	s_waitcnt lgkmcnt(4)
	v_cvt_pk_bf16_f32 v35, v40, v42
	s_waitcnt lgkmcnt(2)
	v_cvt_pk_bf16_f32 v36, v44, v46
	s_waitcnt lgkmcnt(0)
	v_cvt_pk_bf16_f32 v37, v48, v50
	v_lshl_add_u64 v[52:53], v[20:21], 0, v[128:129]
	v_lshlrev_b32_e32 v128, 1, v3
	global_store_dwordx4 v[52:53], v[34:37], off
	v_lshl_add_u64 v[20:21], v[20:21], 0, v[128:129]
	s_nop 0
	v_cvt_pk_bf16_f32 v34, v25, v39
	v_cvt_pk_bf16_f32 v35, v41, v43
	v_cvt_pk_bf16_f32 v36, v45, v47
	v_cvt_pk_bf16_f32 v37, v49, v51
	global_store_dwordx4 v[20:21], v[34:37], off
	s_waitcnt lgkmcnt(0)

; __device__ __forceinline__ unsigned pk2(float lo, float hi) { f32x2_t v = {lo, hi}; bf16x2_t b = __builtin_convertvector(v, bf16x2_t); return __builtin_bit_cast(unsigned, b); }
; __device__ __forceinline__ void transpose_item(const float* W, int K, int N, bf16_t* WT, int mode, float* scr, int item, int lane) {
;     const int nblk = N / 32, kb = item / nblk, nb = item % nblk, k0 = 64 * kb, n0 = 32 * nb;
;     int r0 = n0;
;     if (mode == 1) { r0 = (n0 < FFH) ? (n0 / 128) * 256 + (n0 % 128) : ((n0 - FFH) / 128) * 256 + 128 + ((n0 - FFH) % 128); }
; #pragma unroll 8
;     for (int i = 0; i < 32; ++i) { const int kk = 2 * i + (lane >> 5); scr[kk * 33 + (lane & 31)] = W[(size_t)(k0 + kk) * N + n0 + (lane & 31)]; }
;     asm volatile("s_waitcnt lgkmcnt(0)" ::: "memory");
;     const int c = lane & 7;
; #pragma unroll
;     for (int j = 0; j < 4; ++j) { const int n = (lane >> 3) + 8 * j; const float* s = scr + (8 * c) * 33 + n;
;         u32x4 o; o.x = pk2(s[0 * 33], s[1 * 33]); o.y = pk2(s[2 * 33], s[3 * 33]); o.z = pk2(s[4 * 33], s[5 * 33]); o.w = pk2(s[6 * 33], s[7 * 33]);
;         *(u32x4*)(WT + (size_t)(r0 + n) * K + k0 + 8 * c) = o; }
;     asm volatile("s_waitcnt lgkmcnt(0)" ::: "memory");
.LBB0_1151:
	s_lshl_b32 s15, s9, 1
	s_lshl_b32 s13, s8, 1
	v_or_b32_e32 v34, s15, v22
	v_or_b32_e32 v33, s13, v3
	v_mad_u64_u32 v[34:35], s[18:19], v34, s17, v[20:21]
	v_mad_u64_u32 v[36:37], s[18:19], v33, s17, v[20:21]
	global_load_dword v64, v[34:35], off
	global_load_dword v65, v[36:37], off
	v_or_b32_e32 v25, s13, v1
	v_or_b32_e32 v26, s15, v0
	v_mad_u64_u32 v[66:67], s[18:19], v26, s16, v[2:3]
	v_mad_u64_u32 v[68:69], s[18:19], v25, s16, v[2:3]
	s_add_i32 s19, s15, 4
	s_add_i32 s18, s13, 4
	v_or_b32_e32 v25, s18, v1
	v_or_b32_e32 v26, s19, v0
	s_add_i32 s9, s9, 16
	s_add_i32 s8, s8, 16
	s_add_i32 s12, s12, -16
	v_or_b32_e32 v34, s19, v22
	v_or_b32_e32 v33, s18, v3
	v_mad_u64_u32 v[34:35], s[18:19], v34, s17, v[20:21]
	v_mad_u64_u32 v[36:37], s[18:19], v33, s17, v[20:21]
	global_load_dword v70, v[34:35], off
	global_load_dword v71, v[36:37], off
	v_mad_u64_u32 v[72:73], s[18:19], v26, s16, v[2:3]
	v_mad_u64_u32 v[74:75], s[18:19], v25, s16, v[2:3]
	s_add_i32 s19, s15, 8
	s_add_i32 s18, s13, 8
	v_or_b32_e32 v25, s18, v1
	v_or_b32_e32 v26, s19, v0
	v_or_b32_e32 v34, s19, v22
	v_or_b32_e32 v33, s18, v3
	v_mad_u64_u32 v[34:35], s[18:19], v34, s17, v[20:21]
	v_mad_u64_u32 v[36:37], s[18:19], v33, s17, v[20:21]
	global_load_dword v76, v[34:35], off
	global_load_dword v77, v[36:37], off
	v_mad_u64_u32 v[78:79], s[18:19], v26, s16, v[2:3]
	v_mad_u64_u32 v[80:81], s[18:19], v25, s16, v[2:3]
	s_add_i32 s19, s15, 12
	s_add_i32 s18, s13, 12
	v_or_b32_e32 v25, s18, v1
	v_or_b32_e32 v26, s19, v0
	v_or_b32_e32 v34, s19, v22
	v_or_b32_e32 v33, s18, v3
	v_mad_u64_u32 v[34:35], s[18:19], v34, s17, v[20:21]
	v_mad_u64_u32 v[36:37], s[18:19], v33, s17, v[20:21]
	global_load_dword v82, v[34:35], off
	global_load_dword v83, v[36:37], off
	v_mad_u64_u32 v[84:85], s[18:19], v26, s16, v[2:3]
	v_mad_u64_u32 v[86:87], s[18:19], v25, s16, v[2:3]
	s_add_i32 s19, s15, 16
	s_add_i32 s18, s13, 16
	v_or_b32_e32 v25, s18, v1
	v_or_b32_e32 v26, s19, v0
	v_or_b32_e32 v34, s19, v22
	v_or_b32_e32 v33, s18, v3
	v_mad_u64_u32 v[34:35], s[18:19], v34, s17, v[20:21]
	v_mad_u64_u32 v[36:37], s[18:19], v33, s17, v[20:21]
	global_load_dword v88, v[34:35], off
	global_load_dword v89, v[36:37], off
	v_mad_u64_u32 v[90:91], s[18:19], v26, s16, v[2:3]
	v_mad_u64_u32 v[92:93], s[18:19], v25, s16, v[2:3]
	s_add_i32 s19, s15, 20
	s_add_i32 s18, s13, 20
	v_or_b32_e32 v25, s18, v1
	v_or_b32_e32 v26, s19, v0
	v_or_b32_e32 v34, s19, v22
	v_or_b32_e32 v33, s18, v3
	v_mad_u64_u32 v[34:35], s[18:19], v34, s17, v[20:21]
	v_mad_u64_u32 v[36:37], s[18:19], v33, s17, v[20:21]
	global_load_dword v94, v[34:35], off
	global_load_dword v95, v[36:37], off
	v_mad_u64_u32 v[96:97], s[18:19], v26, s16, v[2:3]
	v_mad_u64_u32 v[98:99], s[18:19], v25, s16, v[2:3]
	s_add_i32 s19, s15, 24
	s_add_i32 s18, s13, 24
	v_or_b32_e32 v25, s18, v1
	v_or_b32_e32 v26, s19, v0
	s_add_i32 s15, s15, 28
	s_add_i32 s13, s13, 28
	s_cmp_lg_u32 s12, 0
	v_or_b32_e32 v34, s19, v22
	v_or_b32_e32 v33, s18, v3
	v_mad_u64_u32 v[34:35], s[18:19], v34, s17, v[20:21]
	v_mad_u64_u32 v[36:37], s[18:19], v33, s17, v[20:21]
	global_load_dword v100, v[34:35], off
	global_load_dword v101, v[36:37], off
	v_mad_u64_u32 v[102:103], s[18:19], v26, s16, v[2:3]
	v_mad_u64_u32 v[104:105], s[18:19], v25, s16, v[2:3]
	v_or_b32_e32 v26, s15, v0
	v_or_b32_e32 v25, s13, v1
	v_or_b32_e32 v34, s15, v22
	v_or_b32_e32 v33, s13, v3
	v_mad_u64_u32 v[34:35], s[18:19], v34, s17, v[20:21]
	v_mad_u64_u32 v[36:37], s[18:19], v33, s17, v[20:21]
	global_load_dword v106, v[34:35], off
	global_load_dword v107, v[36:37], off
	v_mad_u64_u32 v[108:109], s[18:19], v26, s16, v[2:3]
	v_mad_u64_u32 v[110:111], s[18:19], v25, s16, v[2:3]
	s_waitcnt vmcnt(15)
	ds_write_b32 v66, v64
	s_waitcnt vmcnt(14)
	ds_write_b32 v68, v65
	s_waitcnt vmcnt(13)
	ds_write_b32 v72, v70
	s_waitcnt vmcnt(12)
	ds_write_b32 v74, v71
	s_waitcnt vmcnt(11)
	ds_write_b32 v78, v76
	s_waitcnt vmcnt(10)
	ds_write_b32 v80, v77
	s_waitcnt vmcnt(9)
	ds_write_b32 v84, v82
	s_waitcnt vmcnt(8)
	ds_write_b32 v86, v83
	s_waitcnt vmcnt(7)
	ds_write_b32 v90, v88
	s_waitcnt vmcnt(6)
	ds_write_b32 v92, v89
	s_waitcnt vmcnt(5)
	ds_write_b32 v96, v94
	s_waitcnt vmcnt(4)
	ds_write_b32 v98, v95
	s_waitcnt vmcnt(3)
	ds_write_b32 v102, v100
	s_waitcnt vmcnt(2)
	ds_write_b32 v104, v101
	s_waitcnt vmcnt(1)
	ds_write_b32 v108, v106
	s_waitcnt vmcnt(0)
	ds_write_b32 v110, v107
	s_cbranch_scc1 .LBB0_1151
	s_waitcnt lgkmcnt(0)
	v_lshlrev_b32_e32 v128, 1, v24
	ds_read2_b32 v[24:25], v29 offset0:33 offset1:41
	ds_read2_b32 v[38:39], v29 offset1:8
	ds_read2_b32 v[40:41], v29 offset0:66 offset1:74
	ds_read2_b32 v[42:43], v29 offset0:99 offset1:107
	ds_read2_b32 v[44:45], v29 offset0:132 offset1:140
	ds_read2_b32 v[46:47], v29 offset0:165 offset1:173
	ds_read2_b32 v[48:49], v29 offset0:198 offset1:206
	ds_read2_b32 v[50:51], v29 offset0:231 offset1:239
	v_lshl_add_u64 v[20:21], v[6:7], 0, v[128:129]
	v_add_u32_e32 v128, v23, v28
	v_lshlrev_b64 v[52:53], 11, v[128:129]
	s_waitcnt lgkmcnt(6)
	v_cvt_pk_bf16_f32 v34, v38, v24
	s_waitcnt lgkmcnt(4)
	v_cvt_pk_bf16_f32 v35, v40, v42
	s_waitcnt lgkmcnt(2)
	v_cvt_pk_bf16_f32 v36, v44, v46
	s_waitcnt lgkmcnt(0)
	v_cvt_pk_bf16_f32 v37, v48, v50
	v_lshl_add_u64 v[52:53], v[20:21], 0, v[52:53]
	v_add_u32_e32 v128, v23, v30
	global_store_dwordx4 v[52:53], v[34:37], off
	s_nop 1
	v_cvt_pk_bf16_f32 v34, v39, v25
	v_lshlrev_b64 v[24:25], 11, v[128:129]
	v_cvt_pk_bf16_f32 v35, v41, v43
	v_cvt_pk_bf16_f32 v36, v45, v47
	v_cvt_pk_bf16_f32 v37, v49, v51
	v_lshl_add_u64 v[24:25], v[20:21], 0, v[24:25]
	global_store_dwordx4 v[24:25], v[34:37], off
	ds_read2_b32 v[24:25], v29 offset0:49 offset1:57
	ds_read2_b32 v[38:39], v29 offset0:16 offset1:24
	ds_read2_b32 v[40:41], v29 offset0:82 offset1:90
	ds_read2_b32 v[42:43], v29 offset0:115 offset1:123
	ds_read2_b32 v[44:45], v29 offset0:148 offset1:156
	ds_read2_b32 v[46:47], v29 offset0:181 offset1:189
	ds_read2_b32 v[48:49], v29 offset0:214 offset1:222
	ds_read2_b32 v[50:51], v29 offset0:247 offset1:255
	v_add_u32_e32 v128, v23, v31
	v_lshlrev_b64 v[52:53], 11, v[128:129]
	v_add_u32_e32 v128, v23, v32
	s_waitcnt lgkmcnt(6)
	v_cvt_pk_bf16_f32 v34, v38, v24
	s_waitcnt lgkmcnt(4)
	v_cvt_pk_bf16_f32 v35, v40, v42
	s_waitcnt lgkmcnt(2)
	v_cvt_pk_bf16_f32 v36, v44, v46
	s_waitcnt lgkmcnt(0)
	v_cvt_pk_bf16_f32 v37, v48, v50
	v_lshl_add_u64 v[52:53], v[20:21], 0, v[52:53]
	v_lshlrev_b64 v[22:23], 11, v[128:129]
	global_store_dwordx4 v[52:53], v[34:37], off
	v_lshl_add_u64 v[20:21], v[20:21], 0, v[22:23]
	s_nop 0
	v_cvt_pk_bf16_f32 v34, v39, v25
	v_cvt_pk_bf16_f32 v35, v41, v43
	v_cvt_pk_bf16_f32 v36, v45, v47
	v_cvt_pk_bf16_f32 v37, v49, v51
	global_store_dwordx4 v[20:21], v[34:37], off
	s_waitcnt lgkmcnt(0)
	s_or_b64 exec, exec, s[38:39]

; __device__ __forceinline__ void transpose_item(const float* W, int K, int N, bf16_t* WT, int mode, float* scr, int item, int lane) {
;     const int nblk = N / 32, kb = item / nblk, nb = item % nblk, k0 = 64 * kb, n0 = 32 * nb;
;     int r0 = n0;
;     if (mode == 1) { r0 = (n0 < FFH) ? (n0 / 128) * 256 + (n0 % 128) : ((n0 - FFH) / 128) * 256 + 128 + ((n0 - FFH) % 128); }
; #pragma unroll 8
;     for (int i = 0; i < 32; ++i) { const int kk = 2 * i + (lane >> 5); scr[kk * 33 + (lane & 31)] = W[(size_t)(k0 + kk) * N + n0 + (lane & 31)]; }
.LBB0_1155:
	s_lshl_b32 s13, s9, 1
	s_lshl_b32 s12, s8, 1
	v_or_b32_e32 v128, s13, v22
	v_or_b32_e32 v34, s12, v3
	v_mov_b32_e32 v35, v129
	v_lshlrev_b64 v[36:37], 12, v[128:129]
	v_lshlrev_b64 v[34:35], 12, v[34:35]
	v_lshl_add_u64 v[36:37], v[20:21], 0, v[36:37]
	v_lshl_add_u64 v[34:35], v[20:21], 0, v[34:35]
	global_load_dword v64, v[36:37], off
	global_load_dword v65, v[34:35], off
	v_or_b32_e32 v25, s12, v1
	v_or_b32_e32 v26, s13, v0
	v_mad_u64_u32 v[66:67], s[18:19], v26, s16, v[2:3]
	v_mad_u64_u32 v[68:69], s[18:19], v25, s16, v[2:3]
	s_add_i32 s19, s13, 4
	s_add_i32 s18, s12, 4
	v_or_b32_e32 v128, s19, v22
	v_mov_b32_e32 v35, v129
	v_or_b32_e32 v25, s18, v1
	v_or_b32_e32 v26, s19, v0
	s_add_i32 s9, s9, 16
	s_add_i32 s8, s8, 16
	s_add_i32 s15, s15, -16
	v_or_b32_e32 v34, s18, v3
	v_lshlrev_b64 v[36:37], 12, v[128:129]
	v_lshlrev_b64 v[34:35], 12, v[34:35]
	v_lshl_add_u64 v[36:37], v[20:21], 0, v[36:37]
	v_lshl_add_u64 v[34:35], v[20:21], 0, v[34:35]
	global_load_dword v70, v[36:37], off
	global_load_dword v71, v[34:35], off
	v_mad_u64_u32 v[72:73], s[18:19], v26, s16, v[2:3]
	v_mad_u64_u32 v[74:75], s[18:19], v25, s16, v[2:3]
	s_add_i32 s19, s13, 8
	s_add_i32 s18, s12, 8
	v_or_b32_e32 v128, s19, v22
	v_mov_b32_e32 v35, v129
	v_or_b32_e32 v25, s18, v1
	v_or_b32_e32 v26, s19, v0
	v_or_b32_e32 v34, s18, v3
	v_lshlrev_b64 v[36:37], 12, v[128:129]
	v_lshlrev_b64 v[34:35], 12, v[34:35]
	v_lshl_add_u64 v[36:37], v[20:21], 0, v[36:37]
	v_lshl_add_u64 v[34:35], v[20:21], 0, v[34:35]
	global_load_dword v76, v[36:37], off
	global_load_dword v77, v[34:35], off
	v_mad_u64_u32 v[78:79], s[18:19], v26, s16, v[2:3]
	v_mad_u64_u32 v[80:81], s[18:19], v25, s16, v[2:3]
	s_add_i32 s19, s13, 12
	s_add_i32 s18, s12, 12
	v_or_b32_e32 v128, s19, v22
	v_mov_b32_e32 v35, v129
	v_or_b32_e32 v25, s18, v1
	v_or_b32_e32 v26, s19, v0
	v_or_b32_e32 v34, s18, v3
	v_lshlrev_b64 v[36:37], 12, v[128:129]
	v_lshlrev_b64 v[34:35], 12, v[34:35]
	v_lshl_add_u64 v[36:37], v[20:21], 0, v[36:37]
	v_lshl_add_u64 v[34:35], v[20:21], 0, v[34:35]
	global_load_dword v82, v[36:37], off
	global_load_dword v83, v[34:35], off
	v_mad_u64_u32 v[84:85], s[18:19], v26, s16, v[2:3]
	v_mad_u64_u32 v[86:87], s[18:19], v25, s16, v[2:3]
	s_add_i32 s19, s13, 16
	s_add_i32 s18, s12, 16
	v_or_b32_e32 v128, s19, v22
	v_mov_b32_e32 v35, v129
	v_or_b32_e32 v25, s18, v1
	v_or_b32_e32 v26, s19, v0
	v_or_b32_e32 v34, s18, v3
	v_lshlrev_b64 v[36:37], 12, v[128:129]
	v_lshlrev_b64 v[34:35], 12, v[34:35]
	v_lshl_add_u64 v[36:37], v[20:21], 0, v[36:37]
	v_lshl_add_u64 v[34:35], v[20:21], 0, v[34:35]
	global_load_dword v88, v[36:37], off
	global_load_dword v89, v[34:35], off
	v_mad_u64_u32 v[90:91], s[18:19], v26, s16, v[2:3]
	v_mad_u64_u32 v[92:93], s[18:19], v25, s16, v[2:3]
	s_add_i32 s19, s13, 20
	s_add_i32 s18, s12, 20
	v_or_b32_e32 v128, s19, v22
	v_mov_b32_e32 v35, v129
	v_or_b32_e32 v25, s18, v1
	v_or_b32_e32 v26, s19, v0
	v_or_b32_e32 v34, s18, v3
	v_lshlrev_b64 v[36:37], 12, v[128:129]
	v_lshlrev_b64 v[34:35], 12, v[34:35]
	v_lshl_add_u64 v[36:37], v[20:21], 0, v[36:37]
	v_lshl_add_u64 v[34:35], v[20:21], 0, v[34:35]
	global_load_dword v94, v[36:37], off
	global_load_dword v95, v[34:35], off
	v_mad_u64_u32 v[96:97], s[18:19], v26, s16, v[2:3]
	v_mad_u64_u32 v[98:99], s[18:19], v25, s16, v[2:3]
	s_add_i32 s19, s13, 24
	s_add_i32 s18, s12, 24
	v_or_b32_e32 v128, s19, v22
	v_mov_b32_e32 v35, v129
	v_or_b32_e32 v25, s18, v1
	v_or_b32_e32 v26, s19, v0
	s_add_i32 s13, s13, 28
	s_add_i32 s12, s12, 28
	s_cmp_lg_u32 s15, 0
	v_or_b32_e32 v34, s18, v3
	v_lshlrev_b64 v[36:37], 12, v[128:129]
	v_lshlrev_b64 v[34:35], 12, v[34:35]
	v_lshl_add_u64 v[36:37], v[20:21], 0, v[36:37]
	v_lshl_add_u64 v[34:35], v[20:21], 0, v[34:35]
	global_load_dword v100, v[36:37], off
	global_load_dword v101, v[34:35], off
	v_mad_u64_u32 v[102:103], s[18:19], v26, s16, v[2:3]
	v_mad_u64_u32 v[104:105], s[18:19], v25, s16, v[2:3]
	v_or_b32_e32 v128, s13, v22
	v_mov_b32_e32 v35, v129
	v_or_b32_e32 v26, s13, v0
	v_or_b32_e32 v25, s12, v1
	v_or_b32_e32 v34, s12, v3
	v_lshlrev_b64 v[36:37], 12, v[128:129]
	v_lshlrev_b64 v[34:35], 12, v[34:35]
	v_lshl_add_u64 v[36:37], v[20:21], 0, v[36:37]
	v_lshl_add_u64 v[34:35], v[20:21], 0, v[34:35]
	global_load_dword v106, v[36:37], off
	global_load_dword v107, v[34:35], off
	v_mad_u64_u32 v[108:109], s[12:13], v26, s16, v[2:3]
	v_mad_u64_u32 v[110:111], s[12:13], v25, s16, v[2:3]
	s_waitcnt vmcnt(15)
	ds_write_b32 v66, v64
	s_waitcnt vmcnt(14)
	ds_write_b32 v68, v65
	s_waitcnt vmcnt(13)
	ds_write_b32 v72, v70
	s_waitcnt vmcnt(12)
	ds_write_b32 v74, v71
	s_waitcnt vmcnt(11)
	ds_write_b32 v78, v76
	s_waitcnt vmcnt(10)
	ds_write_b32 v80, v77
	s_waitcnt vmcnt(9)
	ds_write_b32 v84, v82
	s_waitcnt vmcnt(8)
	ds_write_b32 v86, v83
	s_waitcnt vmcnt(7)
	ds_write_b32 v90, v88
	s_waitcnt vmcnt(6)
	ds_write_b32 v92, v89
	s_waitcnt vmcnt(5)
	ds_write_b32 v96, v94
	s_waitcnt vmcnt(4)
	ds_write_b32 v98, v95
	s_waitcnt vmcnt(3)
	ds_write_b32 v102, v100
	s_waitcnt vmcnt(2)
	ds_write_b32 v104, v101
	s_waitcnt vmcnt(1)
	ds_write_b32 v108, v106
	s_waitcnt vmcnt(0)
	ds_write_b32 v110, v107
	s_cbranch_scc1 .LBB0_1155
; __device__ __forceinline__ unsigned pk2(float lo, float hi) { f32x2_t v = {lo, hi}; bf16x2_t b = __builtin_convertvector(v, bf16x2_t); return __builtin_bit_cast(unsigned, b); }
; __device__ __forceinline__ void transpose_item(const float* W, int K, int N, bf16_t* WT, int mode, float* scr, int item, int lane) {
;     ...
;     asm volatile("s_waitcnt lgkmcnt(0)" ::: "memory");
;     const int c = lane & 7;
; #pragma unroll
;     for (int j = 0; j < 4; ++j) { const int n = (lane >> 3) + 8 * j; const float* s = scr + (8 * c) * 33 + n;
;         u32x4 o; o.x = pk2(s[0 * 33], s[1 * 33]); o.y = pk2(s[2 * 33], s[3 * 33]); o.z = pk2(s[4 * 33], s[5 * 33]); o.w = pk2(s[6 * 33], s[7 * 33]);
;         *(u32x4*)(WT + (size_t)(r0 + n) * K + k0 + 8 * c) = o; }
;     asm volatile("s_waitcnt lgkmcnt(0)" ::: "memory");
	s_waitcnt lgkmcnt(0)
	v_lshlrev_b32_e32 v128, 1, v24
	ds_read2_b32 v[24:25], v29 offset0:33 offset1:41
	ds_read2_b32 v[38:39], v29 offset1:8
	ds_read2_b32 v[40:41], v29 offset0:66 offset1:74
	ds_read2_b32 v[42:43], v29 offset0:99 offset1:107
	ds_read2_b32 v[44:45], v29 offset0:132 offset1:140
	ds_read2_b32 v[46:47], v29 offset0:165 offset1:173
	ds_read2_b32 v[48:49], v29 offset0:198 offset1:206
	ds_read2_b32 v[50:51], v29 offset0:231 offset1:239
	v_or_b32_e32 v3, v23, v28
	v_lshl_add_u64 v[20:21], v[8:9], 0, v[128:129]
	v_lshlrev_b32_e32 v128, 11, v3
	v_or_b32_e32 v3, v23, v30
	s_waitcnt lgkmcnt(6)
	v_cvt_pk_bf16_f32 v34, v38, v24
	s_waitcnt lgkmcnt(4)
	v_cvt_pk_bf16_f32 v35, v40, v42
	s_waitcnt lgkmcnt(2)
	v_cvt_pk_bf16_f32 v36, v44, v46
	s_waitcnt lgkmcnt(0)
	v_cvt_pk_bf16_f32 v37, v48, v50
	v_lshl_add_u64 v[52:53], v[20:21], 0, v[128:129]
	v_lshlrev_b32_e32 v128, 11, v3
	global_store_dwordx4 v[52:53], v[34:37], off
	v_or_b32_e32 v3, v23, v31
	s_nop 0
	v_cvt_pk_bf16_f32 v34, v39, v25
	v_cvt_pk_bf16_f32 v35, v41, v43
	v_cvt_pk_bf16_f32 v36, v45, v47
	v_cvt_pk_bf16_f32 v37, v49, v51
	v_lshl_add_u64 v[24:25], v[20:21], 0, v[128:129]
	global_store_dwordx4 v[24:25], v[34:37], off
	ds_read2_b32 v[24:25], v29 offset0:49 offset1:57
	ds_read2_b32 v[38:39], v29 offset0:16 offset1:24
	ds_read2_b32 v[40:41], v29 offset0:82 offset1:90
	ds_read2_b32 v[42:43], v29 offset0:115 offset1:123
	ds_read2_b32 v[44:45], v29 offset0:148 offset1:156
	ds_read2_b32 v[46:47], v29 offset0:181 offset1:189
	ds_read2_b32 v[48:49], v29 offset0:214 offset1:222
	ds_read2_b32 v[50:51], v29 offset0:247 offset1:255
	v_lshlrev_b32_e32 v128, 11, v3
	v_or_b32_e32 v3, v23, v32
	s_waitcnt lgkmcnt(6)
	v_cvt_pk_bf16_f32 v34, v38, v24
	s_waitcnt lgkmcnt(4)
	v_cvt_pk_bf16_f32 v35, v40, v42
	s_waitcnt lgkmcnt(2)
	v_cvt_pk_bf16_f32 v36, v44, v46
	s_waitcnt lgkmcnt(0)
	v_cvt_pk_bf16_f32 v37, v48, v50
	v_lshl_add_u64 v[52:53], v[20:21], 0, v[128:129]
	v_lshlrev_b32_e32 v128, 11, v3
	global_store_dwordx4 v[52:53], v[34:37], off
	v_lshl_add_u64 v[20:21], v[20:21], 0, v[128:129]
	s_nop 0
	v_cvt_pk_bf16_f32 v34, v39, v25
	v_cvt_pk_bf16_f32 v35, v41, v43
	v_cvt_pk_bf16_f32 v36, v45, v47
	v_cvt_pk_bf16_f32 v37, v49, v51
	global_store_dwordx4 v[20:21], v[34:37], off
	s_waitcnt lgkmcnt(0)

; __device__ __forceinline__ unsigned pk2(float lo, float hi) { f32x2_t v = {lo, hi}; bf16x2_t b = __builtin_convertvector(v, bf16x2_t); return __builtin_bit_cast(unsigned, b); }
; __device__ __forceinline__ void transpose_item(const float* W, int K, int N, bf16_t* WT, int mode, float* scr, int item, int lane) {
;     const int nblk = N / 32, kb = item / nblk, nb = item % nblk, k0 = 64 * kb, n0 = 32 * nb;
;     int r0 = n0;
;     if (mode == 1) { r0 = (n0 < FFH) ? (n0 / 128) * 256 + (n0 % 128) : ((n0 - FFH) / 128) * 256 + 128 + ((n0 - FFH) % 128); }
; #pragma unroll 8
;     for (int i = 0; i < 32; ++i) { const int kk = 2 * i + (lane >> 5); scr[kk * 33 + (lane & 31)] = W[(size_t)(k0 + kk) * N + n0 + (lane & 31)]; }
;     asm volatile("s_waitcnt lgkmcnt(0)" ::: "memory");
;     const int c = lane & 7;
; #pragma unroll
;     for (int j = 0; j < 4; ++j) { const int n = (lane >> 3) + 8 * j; const float* s = scr + (8 * c) * 33 + n;
;         u32x4 o; o.x = pk2(s[0 * 33], s[1 * 33]); o.y = pk2(s[2 * 33], s[3 * 33]); o.z = pk2(s[4 * 33], s[5 * 33]); o.w = pk2(s[6 * 33], s[7 * 33]);
;         *(u32x4*)(WT + (size_t)(r0 + n) * K + k0 + 8 * c) = o; }
;     asm volatile("s_waitcnt lgkmcnt(0)" ::: "memory");
.LBB0_1160:
	s_lshl_b32 s15, s9, 1
	s_lshl_b32 s13, s8, 1
	v_or_b32_e32 v34, s15, v26
	v_or_b32_e32 v33, s13, v3
	v_mad_i64_i32 v[34:35], s[18:19], v34, s22, v[24:25]
	v_mad_i64_i32 v[36:37], s[18:19], v33, s22, v[24:25]
	global_load_dword v64, v[34:35], off
	global_load_dword v65, v[36:37], off
	v_or_b32_e32 v21, s13, v1
	v_or_b32_e32 v23, s15, v0
	v_mad_u64_u32 v[66:67], s[18:19], v23, s16, v[2:3]
	v_mad_u64_u32 v[68:69], s[18:19], v21, s16, v[2:3]
	s_add_i32 s19, s15, 4
	s_add_i32 s18, s13, 4
	v_or_b32_e32 v21, s18, v1
	v_or_b32_e32 v23, s19, v0
	s_add_i32 s9, s9, 16
	s_add_i32 s8, s8, 16
	s_add_i32 s12, s12, -16
	v_or_b32_e32 v34, s19, v26
	v_or_b32_e32 v33, s18, v3
	v_mad_i64_i32 v[34:35], s[18:19], v34, s22, v[24:25]
	v_mad_i64_i32 v[36:37], s[18:19], v33, s22, v[24:25]
	global_load_dword v70, v[34:35], off
	global_load_dword v71, v[36:37], off
	v_mad_u64_u32 v[72:73], s[18:19], v23, s16, v[2:3]
	v_mad_u64_u32 v[74:75], s[18:19], v21, s16, v[2:3]
	s_add_i32 s19, s15, 8
	s_add_i32 s18, s13, 8
	v_or_b32_e32 v21, s18, v1
	v_or_b32_e32 v23, s19, v0
	v_or_b32_e32 v34, s19, v26
	v_or_b32_e32 v33, s18, v3
	v_mad_i64_i32 v[34:35], s[18:19], v34, s22, v[24:25]
	v_mad_i64_i32 v[36:37], s[18:19], v33, s22, v[24:25]
	global_load_dword v76, v[34:35], off
	global_load_dword v77, v[36:37], off
	v_mad_u64_u32 v[78:79], s[18:19], v23, s16, v[2:3]
	v_mad_u64_u32 v[80:81], s[18:19], v21, s16, v[2:3]
	s_add_i32 s19, s15, 12
	s_add_i32 s18, s13, 12
	v_or_b32_e32 v21, s18, v1
	v_or_b32_e32 v23, s19, v0
	v_or_b32_e32 v34, s19, v26
	v_or_b32_e32 v33, s18, v3
	v_mad_i64_i32 v[34:35], s[18:19], v34, s22, v[24:25]
	v_mad_i64_i32 v[36:37], s[18:19], v33, s22, v[24:25]
	global_load_dword v82, v[34:35], off
	global_load_dword v83, v[36:37], off
	v_mad_u64_u32 v[84:85], s[18:19], v23, s16, v[2:3]
	v_mad_u64_u32 v[86:87], s[18:19], v21, s16, v[2:3]
	s_add_i32 s19, s15, 16
	s_add_i32 s18, s13, 16
	v_or_b32_e32 v21, s18, v1
	v_or_b32_e32 v23, s19, v0
	v_or_b32_e32 v34, s19, v26
	v_or_b32_e32 v33, s18, v3
	v_mad_i64_i32 v[34:35], s[18:19], v34, s22, v[24:25]
	v_mad_i64_i32 v[36:37], s[18:19], v33, s22, v[24:25]
	global_load_dword v88, v[34:35], off
	global_load_dword v89, v[36:37], off
	v_mad_u64_u32 v[90:91], s[18:19], v23, s16, v[2:3]
	v_mad_u64_u32 v[92:93], s[18:19], v21, s16, v[2:3]
	s_add_i32 s19, s15, 20
	s_add_i32 s18, s13, 20
	v_or_b32_e32 v21, s18, v1
	v_or_b32_e32 v23, s19, v0
	v_or_b32_e32 v34, s19, v26
	v_or_b32_e32 v33, s18, v3
	v_mad_i64_i32 v[34:35], s[18:19], v34, s22, v[24:25]
	v_mad_i64_i32 v[36:37], s[18:19], v33, s22, v[24:25]
	global_load_dword v94, v[34:35], off
	global_load_dword v95, v[36:37], off
	v_mad_u64_u32 v[96:97], s[18:19], v23, s16, v[2:3]
	v_mad_u64_u32 v[98:99], s[18:19], v21, s16, v[2:3]
	s_add_i32 s19, s15, 24
	s_add_i32 s18, s13, 24
	v_or_b32_e32 v21, s18, v1
	v_or_b32_e32 v23, s19, v0
	s_add_i32 s15, s15, 28
	s_add_i32 s13, s13, 28
	s_cmp_lg_u32 s12, 0
	v_or_b32_e32 v34, s19, v26
	v_or_b32_e32 v33, s18, v3
	v_mad_i64_i32 v[34:35], s[18:19], v34, s22, v[24:25]
	v_mad_i64_i32 v[36:37], s[18:19], v33, s22, v[24:25]
	global_load_dword v100, v[34:35], off
	global_load_dword v101, v[36:37], off
	v_mad_u64_u32 v[102:103], s[18:19], v23, s16, v[2:3]
	v_mad_u64_u32 v[104:105], s[18:19], v21, s16, v[2:3]
	v_or_b32_e32 v23, s15, v0
	v_or_b32_e32 v21, s13, v1
	v_or_b32_e32 v34, s15, v26
	v_or_b32_e32 v33, s13, v3
	v_mad_i64_i32 v[34:35], s[18:19], v34, s22, v[24:25]
	v_mad_i64_i32 v[36:37], s[18:19], v33, s22, v[24:25]
	global_load_dword v106, v[34:35], off
	global_load_dword v107, v[36:37], off
	v_mad_u64_u32 v[108:109], s[18:19], v23, s16, v[2:3]
	v_mad_u64_u32 v[110:111], s[18:19], v21, s16, v[2:3]
	s_waitcnt vmcnt(15)
	ds_write_b32 v66, v64
	s_waitcnt vmcnt(14)
	ds_write_b32 v68, v65
	s_waitcnt vmcnt(13)
	ds_write_b32 v72, v70
	s_waitcnt vmcnt(12)
	ds_write_b32 v74, v71
	s_waitcnt vmcnt(11)
	ds_write_b32 v78, v76
	s_waitcnt vmcnt(10)
	ds_write_b32 v80, v77
	s_waitcnt vmcnt(9)
	ds_write_b32 v84, v82
	s_waitcnt vmcnt(8)
	ds_write_b32 v86, v83
	s_waitcnt vmcnt(7)
	ds_write_b32 v90, v88
	s_waitcnt vmcnt(6)
	ds_write_b32 v92, v89
	s_waitcnt vmcnt(5)
	ds_write_b32 v96, v94
	s_waitcnt vmcnt(4)
	ds_write_b32 v98, v95
	s_waitcnt vmcnt(3)
	ds_write_b32 v102, v100
	s_waitcnt vmcnt(2)
	ds_write_b32 v104, v101
	s_waitcnt vmcnt(1)
	ds_write_b32 v108, v106
	s_waitcnt vmcnt(0)
	ds_write_b32 v110, v107
	s_cbranch_scc1 .LBB0_1160
	s_waitcnt lgkmcnt(0)
	ds_read2_b32 v[36:37], v29 offset0:33 offset1:41
	ds_read2_b32 v[38:39], v29 offset1:8
	ds_read2_b32 v[40:41], v29 offset0:66 offset1:74
	ds_read2_b32 v[42:43], v29 offset0:99 offset1:107
	ds_read2_b32 v[44:45], v29 offset0:132 offset1:140
	ds_read2_b32 v[46:47], v29 offset0:165 offset1:173
	ds_read2_b32 v[48:49], v29 offset0:198 offset1:206
	ds_read2_b32 v[50:51], v29 offset0:231 offset1:239
	v_or_b32_e32 v52, v20, v28
	v_ashrrev_i32_e32 v23, 31, v22
	v_ashrrev_i32_e32 v53, 31, v52
	v_lshl_add_u64 v[34:35], v[22:23], 1, v[10:11]
	v_lshlrev_b64 v[52:53], 11, v[52:53]
	s_waitcnt lgkmcnt(6)
	v_cvt_pk_bf16_f32 v22, v38, v36
	s_waitcnt lgkmcnt(4)
	v_cvt_pk_bf16_f32 v23, v40, v42
	s_waitcnt lgkmcnt(2)
	v_cvt_pk_bf16_f32 v24, v44, v46
	s_waitcnt lgkmcnt(0)
	v_cvt_pk_bf16_f32 v25, v48, v50
	v_lshl_add_u64 v[52:53], v[34:35], 0, v[52:53]
	v_or_b32_e32 v36, v20, v30
	global_store_dwordx4 v[52:53], v[22:25], off
	v_or_b32_e32 v52, v20, v31
	v_ashrrev_i32_e32 v53, 31, v52
	v_cvt_pk_bf16_f32 v22, v39, v37
	v_ashrrev_i32_e32 v37, 31, v36
	v_lshlrev_b64 v[36:37], 11, v[36:37]
	v_cvt_pk_bf16_f32 v23, v41, v43
	v_cvt_pk_bf16_f32 v24, v45, v47
	v_cvt_pk_bf16_f32 v25, v49, v51
	v_lshl_add_u64 v[36:37], v[34:35], 0, v[36:37]
	global_store_dwordx4 v[36:37], v[22:25], off
	ds_read2_b32 v[36:37], v29 offset0:49 offset1:57
	ds_read2_b32 v[38:39], v29 offset0:16 offset1:24
	ds_read2_b32 v[40:41], v29 offset0:82 offset1:90
	ds_read2_b32 v[42:43], v29 offset0:115 offset1:123
	ds_read2_b32 v[44:45], v29 offset0:148 offset1:156
	ds_read2_b32 v[46:47], v29 offset0:181 offset1:189
	ds_read2_b32 v[48:49], v29 offset0:214 offset1:222
	ds_read2_b32 v[50:51], v29 offset0:247 offset1:255
	v_or_b32_e32 v20, v20, v32
	v_lshlrev_b64 v[52:53], 11, v[52:53]
	v_ashrrev_i32_e32 v21, 31, v20
	s_waitcnt lgkmcnt(6)
	v_cvt_pk_bf16_f32 v22, v38, v36
	s_waitcnt lgkmcnt(4)
	v_cvt_pk_bf16_f32 v23, v40, v42
	s_waitcnt lgkmcnt(2)
	v_cvt_pk_bf16_f32 v24, v44, v46
	s_waitcnt lgkmcnt(0)
	v_cvt_pk_bf16_f32 v25, v48, v50
	v_lshl_add_u64 v[52:53], v[34:35], 0, v[52:53]
	v_lshlrev_b64 v[20:21], 11, v[20:21]
	global_store_dwordx4 v[52:53], v[22:25], off
	v_lshl_add_u64 v[20:21], v[34:35], 0, v[20:21]
	s_nop 0
	v_cvt_pk_bf16_f32 v22, v39, v37
	v_cvt_pk_bf16_f32 v23, v41, v43
	v_cvt_pk_bf16_f32 v24, v45, v47
	v_cvt_pk_bf16_f32 v25, v49, v51
	global_store_dwordx4 v[20:21], v[22:25], off
	s_waitcnt lgkmcnt(0)
	s_branch .LBB0_1138
